# P1 row loop: rows 1 and half of row 2 issued with row 0 at the loop head; conservative vmcnt drain replaced by vmcnt(12) waits at each row's first use
# speedup vs baseline: 1.0049x; 1.0003x over previous
; DI void phase1(const Params& p, unsigned char* smem) {
;     ...
;     float4 gw0[16], gw1[16];
; #pragma unroll
;     for (int i = 0; i < 4; ++i)
; #pragma unroll
;         for (int e = 0; e < 4; ++e) {
;             const float* wp = p.in[4] + (size_t)(i * 256 + lane * 4 + e) * 4616 + 2048;
;             gw0[i * 4 + e] = *(const float4*)wp; gw1[i * 4 + e] = *(const float4*)(wp + 4);
;         }
;     float* ig = (float*)(ws + OFF_IG);
;     float* lf = (float*)(ws + OFF_LOGF);
;     for (int row0 = (blockIdx.x * 8 + wid) * 4; row0 < T_; row0 += gridDim.x * 32) {
.LBB0_184:
	s_or_b64 exec, exec, s[0:1]
	s_add_u32 s62, s70, 0x2000000
	s_addc_u32 s63, s71, 0
	s_add_u32 s94, s70, 0x4000000
	s_addc_u32 s95, s71, 0
	s_add_u32 s88, s70, 0x325c000
	v_mov_b32_e32 v0, v250
	s_addc_u32 s89, s71, 0
	s_waitcnt lgkmcnt(0)
	s_barrier
	v_lshlrev_b32_e32 v150, 4, v250
	v_add_u32_e32 v151, 0x6000, v150
	v_add_u32_e32 v152, 0xc000, v150
	v_add_u32_e32 v153, 0x12000, v150
	global_load_dwordx4 v[156:159], v150, s[62:63]
	global_load_dwordx4 v[160:163], v151, s[62:63]
	global_load_dwordx4 v[164:167], v152, s[62:63]
	global_load_dwordx4 v[168:171], v153, s[62:63]
	s_waitcnt vmcnt(3)
	ds_write_b128 v150, v[156:159] offset:1024
	s_waitcnt vmcnt(2)
	ds_write_b128 v150, v[160:163] offset:9216
	s_waitcnt vmcnt(1)
	ds_write_b128 v150, v[164:167] offset:17408
	s_waitcnt vmcnt(0)
	ds_write_b128 v150, v[168:171] offset:25600
	s_waitcnt lgkmcnt(0)
	s_barrier
	s_add_u32 s20, s70, 0x32dc000
	v_ashrrev_i32_e32 v1, 4, v0
	s_addc_u32 s21, s71, 0
	s_lshl_b32 s0, s2, 5
	v_and_b32_e32 v1, -4, v1
	v_writelane_b32 v254, s0, 52
	v_add_u32_e32 v176, s0, v1
	s_mov_b32 s0, 0x8000
	v_cmp_gt_i32_e32 vcc, s0, v176
	s_and_saveexec_b64 s[22:23], vcc
	s_cbranch_execz .LBB0_219
	v_and_b32_e32 v230, 63, v0
	v_readfirstlane_b32 s4, v0
	v_readlane_b32 s36, v254, 4
	v_mov_b32_e32 v179, 0
	v_readlane_b32 s44, v254, 12
	v_readlane_b32 s45, v254, 13
	s_lshr_b32 s4, s4, 6
	s_lshr_b32 s5, s4, 1
	s_and_b32 s6, s4, 1
	s_mul_i32 s5, s5, 0x482000
	s_mul_i32 s6, s6, 0x9040
	s_add_i32 s5, s5, s6
	s_add_i32 s5, s5, 0x2000
	s_add_u32 s8, s44, s5
	s_addc_u32 s9, s45, 0
	s_add_u32 s10, s8, 0x4820
	s_addc_u32 s11, s9, 0
	v_mul_u32_u24_e32 v168, 0x12080, v230
	v_lshlrev_b32_e32 v128, 2, v230
	v_or_b32_e32 v130, 0x100, v128
	s_mov_b64 s[16:17], 0x2000
	global_load_dwordx4 v[152:155], v168, s[8:9]
	global_load_dwordx4 v[156:159], v168, s[8:9] offset:16
	global_load_dwordx4 v[160:163], v168, s[10:11]
	global_load_dwordx4 v[164:167], v168, s[10:11] offset:16
	v_lshlrev_b32_e32 v170, 4, v230
	s_lshl_b32 s6, s4, 12
	v_add_u32_e32 v169, s6, v170
	v_add_u32_e32 v170, 0x8800, v170
	s_waitcnt vmcnt(3)
	ds_write_b128 v169, v[152:155] offset:34816
	s_waitcnt vmcnt(2)
	ds_write_b128 v169, v[156:159] offset:35840
	s_waitcnt vmcnt(1)
	ds_write_b128 v169, v[160:163] offset:36864
	s_waitcnt vmcnt(0)
	ds_write_b128 v169, v[164:167] offset:37888
	s_waitcnt lgkmcnt(0)
	s_barrier
	ds_read_b128 v[0:3], v170
	ds_read_b128 v[4:7], v170 offset:1024
	ds_read_b128 v[8:11], v170 offset:2048
	ds_read_b128 v[12:15], v170 offset:3072
	ds_read_b128 v[16:19], v170 offset:4096
	ds_read_b128 v[20:23], v170 offset:5120
	ds_read_b128 v[24:27], v170 offset:6144
	ds_read_b128 v[28:31], v170 offset:7168
	ds_read_b128 v[32:35], v170 offset:8192
	ds_read_b128 v[36:39], v170 offset:9216
	ds_read_b128 v[40:43], v170 offset:10240
	ds_read_b128 v[44:47], v170 offset:11264
	ds_read_b128 v[48:51], v170 offset:12288
	ds_read_b128 v[52:55], v170 offset:13312
	ds_read_b128 v[56:59], v170 offset:14336
	ds_read_b128 v[60:63], v170 offset:15360
	ds_read_b128 v[64:67], v170 offset:16384
	ds_read_b128 v[68:71], v170 offset:17408
	ds_read_b128 v[72:75], v170 offset:18432
	ds_read_b128 v[76:79], v170 offset:19456
	ds_read_b128 v[80:83], v170 offset:20480
	ds_read_b128 v[84:87], v170 offset:21504
	ds_read_b128 v[88:91], v170 offset:22528
	ds_read_b128 v[92:95], v170 offset:23552
	ds_read_b128 v[96:99], v170 offset:24576
	ds_read_b128 v[100:103], v170 offset:25600
	ds_read_b128 v[104:107], v170 offset:26624
	ds_read_b128 v[108:111], v170 offset:27648
	ds_read_b128 v[112:115], v170 offset:28672
	ds_read_b128 v[116:119], v170 offset:29696
	ds_read_b128 v[120:123], v170 offset:30720
	ds_read_b128 v[124:127], v170 offset:31744
	s_waitcnt lgkmcnt(0)
	v_readlane_b32 s37, v254, 5
	v_readlane_b32 s46, v254, 14
	v_readlane_b32 s47, v254, 15
	v_mov_b32_e32 v129, v179
	v_lshlrev_b32_e32 v178, 4, v230
	v_readlane_b32 s38, v254, 6
	v_readlane_b32 s39, v254, 7
	v_readlane_b32 s40, v254, 8
	v_or_b32_e32 v132, 0x200, v128
	v_or_b32_e32 v134, 0x300, v128
	v_subrev_co_u32_e64 v231, s[0:1], 4, v230
	v_lshl_add_u64 v[180:181], s[36:37], 0, v[178:179]
	v_lshl_add_u64 v[136:137], s[46:47], 0, v[128:129]
	v_lshlrev_b32_e32 v178, 3, v230
	v_cmp_gt_u32_e32 vcc, 8, v230
	s_xor_b64 s[24:25], s[0:1], -1
	s_lshl_b32 s3, s33, 5
	v_cmp_eq_u32_e64 s[0:1], 1, v230
	v_cmp_eq_u32_e64 s[14:15], 2, v230
	v_cmp_eq_u32_e64 s[4:5], 3, v230
	v_cmp_eq_u32_e64 s[6:7], 4, v230
	v_cmp_eq_u32_e64 s[8:9], 5, v230
	v_cmp_eq_u32_e64 s[10:11], 6, v230
	v_cmp_eq_u32_e64 s[12:13], 7, v230
	v_lshl_add_u64 v[182:183], v[136:137], 0, s[16:17]
	v_lshl_add_u64 v[184:185], s[94:95], 0, v[178:179]
	s_mov_b64 s[26:27], 0
	v_lshlrev_b32_e32 v178, 2, v128
	v_lshlrev_b32_e32 v186, 2, v130
	v_lshlrev_b32_e32 v188, 2, v132
	v_lshlrev_b32_e32 v190, 2, v134
	v_mov_b32_e32 v232, 0x3727c5ac
	s_mov_b32 s36, 0x800000
	s_mov_b32 s37, 0x3f2aaaab
	v_mov_b32_e32 v233, 0x3ecc95a3
	s_mov_b32 s38, 0x3f317218
	s_mov_b32 s39, 0x7f800000
	s_mov_b32 s40, 0x33800000
	v_mov_b32_e32 v234, 0x7f800000
	v_mov_b32_e32 v235, 0x7fc00000
	v_mov_b32_e32 v236, 0xff800000
	v_mov_b32_e32 v192, 0x3f317218
	v_readlane_b32 s41, v254, 9
	v_readlane_b32 s42, v254, 10
	v_readlane_b32 s43, v254, 11
	v_readlane_b32 s48, v254, 16
	v_readlane_b32 s49, v254, 17
	v_readlane_b32 s50, v254, 18
	v_readlane_b32 s51, v254, 19
	global_load_dword v251, v[182:183], off
	s_mov_b64 s[76:77], 0x1000
	s_mov_b64 s[78:79], 0x2000
	s_branch .LBB0_189

; DI void row_stats(const float (&v)[16], float& mean, float& rstd) {
;     float s = 0.f;
; #pragma unroll
;     for (int i = 0; i < 16; ++i) s += v[i];
;     mean = wsum(s) * (1.f / 1024.f);
;     float q = 0.f;
; #pragma unroll
;     for (int i = 0; i < 16; ++i) { float d = v[i] - mean; q += d * d; }
;     rstd = rsqrtf(wsum(q) * (1.f / 1024.f) + 1e-5f);
; }
; DI void phase1(const Params& p, unsigned char* smem) {
;     ...
;     for (int row0 = (blockIdx.x * 8 + wid) * 4; row0 < T_; row0 += gridDim.x * 32) {
;         float vv[4][16];
; #pragma unroll
;         for (int rr = 0; rr < 4; ++rr)
; #pragma unroll
;             for (int i = 0; i < 4; ++i) { float4 t = *(const float4*)(p.in[0] + (size_t)(row0 + rr) * 1024 + i * 256 + lane * 4); vv[rr][4 * i] = t.x; vv[rr][4 * i + 1] = t.y; vv[rr][4 * i + 2] = t.z; vv[rr][4 * i + 3] = t.w; }
; #pragma unroll
;         for (int rr = 0; rr < 4; ++rr) {
;             const int row = row0 + rr;
;             float mean, rstd; row_stats(vv[rr], mean, rstd);
.LBB0_189:
	v_ashrrev_i32_e32 v177, 31, v176
	v_lshlrev_b64 v[128:129], 12, v[176:177]
	v_lshl_add_u64 v[140:141], v[180:181], 0, v[128:129]
	global_load_dwordx4 v[128:131], v[140:141], off
	global_load_dwordx4 v[132:135], v[140:141], off offset:1024
	global_load_dwordx4 v[136:139], v[140:141], off offset:2048
	v_lshl_add_u64 v[182:183], v[140:141], 0, s[76:77]
	v_lshl_add_u64 v[252:253], v[140:141], 0, s[78:79]
	s_nop 0
	global_load_dwordx4 v[140:143], v[140:141], off offset:3072
	global_load_dwordx4 v[172:175], v[182:183], off
	global_load_dwordx4 v[168:171], v[182:183], off offset:1024
	global_load_dwordx4 v[164:167], v[182:183], off offset:2048
	global_load_dwordx4 v[160:163], v[182:183], off offset:3072
	global_load_dwordx4 v[156:159], v[252:253], off
	global_load_dwordx4 v[152:155], v[252:253], off offset:1024
	v_ashrrev_i32_e32 v193, 13, v176
	v_lshl_add_u32 v237, v193, 13, v178
	v_add_u32_e32 v212, 1, v176
	v_add_u32_e32 v202, 2, v176
	v_add_u32_e32 v194, 3, v176
	v_ashrrev_i32_e32 v213, 31, v212
	v_ashrrev_i32_e32 v203, 31, v202
	v_ashrrev_i32_e32 v195, 31, v194
	v_mov_b32_e32 v187, v179
	v_mov_b32_e32 v189, v179
	v_mov_b32_e32 v191, v179
	s_waitcnt vmcnt(9)
	v_add_f32_e32 v144, 0, v128
	v_add_f32_e32 v144, v144, v129
	v_add_f32_e32 v144, v144, v130
	v_add_f32_e32 v144, v144, v131
	s_waitcnt vmcnt(8)
	v_add_f32_e32 v144, v144, v132
	v_add_f32_e32 v144, v144, v133
	v_add_f32_e32 v144, v144, v134
	v_add_f32_e32 v144, v144, v135
	s_waitcnt vmcnt(7)
	v_add_f32_e32 v144, v144, v136
	v_add_f32_e32 v144, v144, v137
	v_add_f32_e32 v144, v144, v138
	v_add_f32_e32 v144, v144, v139
	s_waitcnt vmcnt(6)
	v_add_f32_e32 v144, v144, v140
	v_add_f32_e32 v144, v144, v141
	v_add_f32_e32 v144, v144, v142
	v_add_f32_e32 v144, v144, v143
	s_nop 1
	v_add_f32_dpp v144, v144, v144 quad_perm:[1,0,3,2] row_mask:0xf bank_mask:0xf bound_ctrl:1
	s_nop 1
	v_add_f32_dpp v144, v144, v144 quad_perm:[2,3,0,1] row_mask:0xf bank_mask:0xf bound_ctrl:1
	s_nop 1
	v_add_f32_dpp v144, v144, v144 row_half_mirror row_mask:0xf bank_mask:0xf bound_ctrl:1
	s_nop 1
	v_add_f32_dpp v144, v144, v144 row_mirror row_mask:0xf bank_mask:0xf bound_ctrl:1
	s_nop 0
	v_readlane_b32 s17, v144, 16
	v_readlane_b32 s16, v144, 0
	v_readlane_b32 s18, v144, 32
	v_readlane_b32 s19, v144, 48
	v_mov_b32_e32 v144, s17
	v_add_f32_e32 v144, s16, v144
	v_add_f32_e32 v144, s18, v144
	v_add_f32_e32 v144, s19, v144
	v_mul_f32_e32 v144, 0x3a800000, v144
	v_pk_add_f32 v[146:147], v[128:129], v[144:145] op_sel_hi:[1,0] neg_lo:[0,1] neg_hi:[0,1]
	v_mul_i32_i24_e32 v128, 0x1800, v193
	v_ashrrev_i32_e32 v129, 31, v128
	v_pk_add_f32 v[222:223], v[132:133], v[144:145] op_sel_hi:[1,0] neg_lo:[0,1] neg_hi:[0,1]
	v_lshl_add_u64 v[132:133], v[128:129], 2, s[62:63]
	s_mov_b64 s[16:17], 0x1000
	v_lshl_add_u64 v[216:217], v[132:133], 0, s[16:17]
	v_lshl_add_u64 v[198:199], v[216:217], 0, v[178:179]
	v_pk_add_f32 v[148:149], v[130:131], v[144:145] op_sel_hi:[1,0] neg_lo:[0,1] neg_hi:[0,1]
	ds_read_b128 v[128:131], v237 offset:5120
	v_pk_add_f32 v[206:207], v[134:135], v[144:145] op_sel_hi:[1,0] neg_lo:[0,1] neg_hi:[0,1]
	v_pk_add_f32 v[214:215], v[136:137], v[144:145] op_sel_hi:[1,0] neg_lo:[0,1] neg_hi:[0,1]
	v_pk_add_f32 v[210:211], v[138:139], v[144:145] op_sel_hi:[1,0] neg_lo:[0,1] neg_hi:[0,1]
	v_pk_add_f32 v[200:201], v[140:141], v[144:145] op_sel_hi:[1,0] neg_lo:[0,1] neg_hi:[0,1]
	v_pk_add_f32 v[208:209], v[142:143], v[144:145] op_sel_hi:[1,0] neg_lo:[0,1] neg_hi:[0,1]
	v_lshl_add_u64 v[196:197], v[132:133], 0, v[178:179]
	s_waitcnt lgkmcnt(0)
	v_pk_add_f32 v[134:135], v[128:129], 1.0 op_sel_hi:[1,0]
	v_pk_mul_f32 v[128:129], v[146:147], v[146:147]
	v_pk_add_f32 v[136:137], v[130:131], 1.0 op_sel_hi:[1,0]
	v_add_f32_e32 v130, v128, v129
	v_pk_mul_f32 v[128:129], v[148:149], v[148:149]
	s_nop 0
	v_add_f32_e32 v128, v128, v130
	v_add_f32_e32 v130, v129, v128
	v_pk_mul_f32 v[128:129], v[222:223], v[222:223]
	s_nop 0
	v_add_f32_e32 v128, v128, v130
	v_add_f32_e32 v130, v129, v128
	v_pk_mul_f32 v[128:129], v[206:207], v[206:207]
	s_nop 0
	v_add_f32_e32 v128, v128, v130
	v_add_f32_e32 v130, v129, v128
	v_pk_mul_f32 v[128:129], v[214:215], v[214:215]
	s_nop 0
	v_add_f32_e32 v128, v128, v130
	v_add_f32_e32 v130, v129, v128
	v_pk_mul_f32 v[128:129], v[210:211], v[210:211]
	s_nop 0
	v_add_f32_e32 v128, v128, v130
	v_add_f32_e32 v130, v129, v128
	v_pk_mul_f32 v[128:129], v[200:201], v[200:201]
	s_nop 0
	v_add_f32_e32 v128, v128, v130
	v_add_f32_e32 v130, v129, v128
	v_pk_mul_f32 v[128:129], v[208:209], v[208:209]
	s_nop 0
	v_add_f32_e32 v128, v128, v130
	v_add_f32_e32 v128, v129, v128
	s_nop 1
	v_add_f32_dpp v128, v128, v128 quad_perm:[1,0,3,2] row_mask:0xf bank_mask:0xf bound_ctrl:1
	s_nop 1
	v_add_f32_dpp v128, v128, v128 quad_perm:[2,3,0,1] row_mask:0xf bank_mask:0xf bound_ctrl:1
	s_nop 1
	v_add_f32_dpp v128, v128, v128 row_half_mirror row_mask:0xf bank_mask:0xf bound_ctrl:1
	s_nop 1
	v_add_f32_dpp v128, v128, v128 row_mirror row_mask:0xf bank_mask:0xf bound_ctrl:1
	s_nop 0
	v_readlane_b32 s17, v128, 16
	v_readlane_b32 s16, v128, 0
	v_readlane_b32 s18, v128, 32
	v_readlane_b32 s19, v128, 48
	v_mov_b32_e32 v128, s17
	v_add_f32_e32 v128, s16, v128
	v_add_f32_e32 v128, s18, v128
	v_add_f32_e32 v128, s19, v128
	v_fmamk_f32 v128, v128, 0x3a800000, v232
	v_mul_f32_e32 v129, 0x4b800000, v128
	v_cmp_gt_f32_e64 s[16:17], s36, v128
	s_nop 1
	v_cndmask_b32_e64 v128, v128, v129, s[16:17]
	v_rsq_f32_e32 v128, v128
	s_nop 0
	v_mul_f32_e32 v129, 0x45800000, v128
	v_cndmask_b32_e64 v224, v128, v129, s[16:17]
	ds_read_b128 v[128:131], v237 offset:1024
	v_pk_mul_f32 v[132:133], v[146:147], v[224:225] op_sel_hi:[1,0]
	v_pk_mul_f32 v[222:223], v[222:223], v[224:225] op_sel_hi:[1,0]
	v_pk_mul_f32 v[206:207], v[206:207], v[224:225] op_sel_hi:[1,0]
	v_pk_mul_f32 v[214:215], v[214:215], v[224:225] op_sel_hi:[1,0]
	v_pk_mul_f32 v[210:211], v[210:211], v[224:225] op_sel_hi:[1,0]
	v_pk_mul_f32 v[200:201], v[200:201], v[224:225] op_sel_hi:[1,0]
	s_waitcnt lgkmcnt(0)
; DI uint2 pk4(f32x4 v) { return make_uint2(pk2(v[0], v[1]), pk2(v[2], v[3])); }
; DI void phase1(const Params& p, unsigned char* smem) {
;     ...
;             for (int i = 0; i < 4; ++i) {
;                 int c = i * 256 + lane * 4;
;                 float4 sh = *(const float4*)(mb + c), sc = *(const float4*)(mb + 1024 + c);
;                 f32x4 o;
;                 o[0] = (vv[rr][4 * i] - mean) * rstd * (1.f + sc.x) + sh.x;
;                 o[1] = (vv[rr][4 * i + 1] - mean) * rstd * (1.f + sc.y) + sh.y;
;                 o[2] = (vv[rr][4 * i + 2] - mean) * rstd * (1.f + sc.z) + sh.z;
;                 o[3] = (vv[rr][4 * i + 3] - mean) * rstd * (1.f + sc.w) + sh.w;
;                 *(uint2*)(h1 + (size_t)row * 1024 + c) = pk4(o);
; #pragma unroll
;                 for (int e = 0; e < 4; ++e) {
;                     const float4 w0 = gw0[i * 4 + e], w1 = gw1[i * 4 + e];
;                     ga[0] += o[e] * w0.x; ga[1] += o[e] * w0.y; ga[2] += o[e] * w0.z; ga[3] += o[e] * w0.w;
;                     ga[4] += o[e] * w1.x; ga[5] += o[e] * w1.y; ga[6] += o[e] * w1.z; ga[7] += o[e] * w1.w;
;                 }
	v_pk_fma_f32 v[220:221], v[134:135], v[132:133], v[128:129]
	v_pk_mul_f32 v[128:129], v[148:149], v[224:225] op_sel_hi:[1,0]
	v_lshlrev_b64 v[132:133], 12, v[194:195]
	v_pk_fma_f32 v[218:219], v[136:137], v[128:129], v[130:131]
	v_lshlrev_b64 v[128:129], 11, v[176:177]
	v_lshl_add_u64 v[226:227], v[184:185], 0, v[128:129]
	v_lshlrev_b64 v[128:129], 12, v[212:213]
	v_lshlrev_b64 v[130:131], 12, v[202:203]
	v_lshl_add_u64 v[128:129], v[180:181], 0, v[128:129]
	v_lshl_add_u64 v[130:131], v[180:181], 0, v[130:131]
	v_lshl_add_u64 v[204:205], v[180:181], 0, v[132:133]
	v_cvt_pk_bf16_f32 v228, v220, v221
	v_cvt_pk_bf16_f32 v229, v218, v219
	global_load_dwordx4 v[148:151], v[130:131], off offset:2048
	global_load_dwordx4 v[144:147], v[130:131], off offset:3072
	global_load_dwordx4 v[140:143], v[204:205], off
	global_load_dwordx4 v[136:139], v[204:205], off offset:1024
	global_load_dwordx4 v[132:135], v[204:205], off offset:2048
	s_nop 0
	global_load_dwordx4 v[128:131], v[204:205], off offset:3072
	v_lshl_add_u64 v[204:205], v[216:217], 0, v[186:187]
	global_store_dwordx2 v[226:227], v[228:229], off
	ds_read_b128 v[238:241], v237 offset:6144
	v_fma_f32 v177, v0, v220, 0
	v_fmac_f32_e32 v177, v8, v221
	v_fmac_f32_e32 v177, v16, v218
	v_fmac_f32_e32 v177, v24, v219
	v_fma_f32 v187, v1, v220, 0
	v_fmac_f32_e32 v187, v9, v221
	v_fmac_f32_e32 v187, v17, v218
	v_fmac_f32_e32 v187, v25, v219
	s_waitcnt lgkmcnt(0)
	v_pk_add_f32 v[228:229], v[238:239], 1.0 op_sel_hi:[1,0]
	v_pk_add_f32 v[242:243], v[240:241], 1.0 op_sel_hi:[1,0]
	ds_read_b128 v[238:241], v237 offset:2048
	s_waitcnt lgkmcnt(0)
	v_pk_fma_f32 v[228:229], v[222:223], v[228:229], v[238:239]
	v_pk_fma_f32 v[222:223], v[206:207], v[242:243], v[240:241]
	v_cvt_pk_bf16_f32 v206, v228, v229
	v_cvt_pk_bf16_f32 v207, v222, v223
	global_store_dwordx2 v[226:227], v[206:207], off offset:512
	v_lshl_add_u64 v[206:207], v[216:217], 0, v[188:189]
	ds_read_b128 v[238:241], v237 offset:7168
	v_fmac_f32_e32 v177, v32, v228
	v_fmac_f32_e32 v177, v40, v229
	v_fmac_f32_e32 v177, v48, v222
	v_fmac_f32_e32 v177, v56, v223
	v_fma_f32 v189, v2, v220, 0
	v_fmac_f32_e32 v187, v33, v228
	v_fmac_f32_e32 v189, v10, v221
	v_fmac_f32_e32 v187, v41, v229
	v_fmac_f32_e32 v189, v18, v218
	v_fmac_f32_e32 v187, v49, v222
	v_fmac_f32_e32 v189, v26, v219
	v_fmac_f32_e32 v187, v57, v223
	v_fmac_f32_e32 v189, v34, v228
	v_fmac_f32_e32 v189, v42, v229
	v_fmac_f32_e32 v189, v50, v222
	v_fmac_f32_e32 v189, v58, v223
	s_waitcnt lgkmcnt(0)
	v_pk_add_f32 v[242:243], v[238:239], 1.0 op_sel_hi:[1,0]
	v_pk_add_f32 v[244:245], v[240:241], 1.0 op_sel_hi:[1,0]
	ds_read_b128 v[238:241], v237 offset:3072
	s_waitcnt lgkmcnt(0)
	v_pk_fma_f32 v[238:239], v[214:215], v[242:243], v[238:239]
	v_pk_fma_f32 v[210:211], v[210:211], v[244:245], v[240:241]
	v_pk_mul_f32 v[240:241], v[208:209], v[224:225] op_sel_hi:[1,0]
	v_cvt_pk_bf16_f32 v208, v238, v239
	v_cvt_pk_bf16_f32 v209, v210, v211
	global_store_dwordx2 v[226:227], v[208:209], off offset:1024
	v_lshl_add_u64 v[208:209], v[216:217], 0, v[190:191]
	ds_read_b128 v[214:217], v237 offset:8192
	v_fmac_f32_e32 v177, v64, v238
	v_fmac_f32_e32 v177, v72, v239
	v_fmac_f32_e32 v177, v80, v210
	v_fmac_f32_e32 v177, v88, v211
	v_fma_f32 v191, v3, v220, 0
	v_fmac_f32_e32 v187, v65, v238
	v_fmac_f32_e32 v191, v11, v221
	v_fmac_f32_e32 v187, v73, v239
	v_fmac_f32_e32 v191, v19, v218
	v_fmac_f32_e32 v187, v81, v210
	v_fmac_f32_e32 v191, v27, v219
	v_fmac_f32_e32 v187, v89, v211
	v_fmac_f32_e32 v191, v35, v228
	v_fmac_f32_e32 v189, v66, v238
	v_fmac_f32_e32 v191, v43, v229
	v_fmac_f32_e32 v189, v74, v239
	v_fmac_f32_e32 v191, v51, v222
	v_fmac_f32_e32 v189, v82, v210
	v_fmac_f32_e32 v191, v59, v223
	v_fmac_f32_e32 v189, v90, v211
	v_fmac_f32_e32 v191, v67, v238
	v_fmac_f32_e32 v191, v75, v239
	v_fmac_f32_e32 v191, v83, v210
	v_fmac_f32_e32 v191, v91, v211
	v_fma_f32 v224, v6, v220, 0
	v_fmac_f32_e32 v224, v14, v221
	v_fmac_f32_e32 v224, v22, v218
	v_fmac_f32_e32 v224, v30, v219
	v_fmac_f32_e32 v224, v38, v228
	v_fmac_f32_e32 v224, v46, v229
	v_fmac_f32_e32 v224, v54, v222
	v_fmac_f32_e32 v224, v62, v223
	v_fmac_f32_e32 v224, v70, v238
	v_fmac_f32_e32 v224, v78, v239
	v_fmac_f32_e32 v224, v86, v210
	v_fmac_f32_e32 v224, v94, v211
	s_waitcnt lgkmcnt(0)
	v_pk_add_f32 v[242:243], v[214:215], 1.0 op_sel_hi:[1,0]
	v_pk_add_f32 v[244:245], v[216:217], 1.0 op_sel_hi:[1,0]
	ds_read_b128 v[214:217], v237 offset:4096
	s_waitcnt lgkmcnt(0)
; DI uint2 pk4(f32x4 v) { return make_uint2(pk2(v[0], v[1]), pk2(v[2], v[3])); }
; DI float wsum(float v) {
;     v += dpp_f(v, 0); v += dpp_f(v, 1); v += dpp_f(v, 2); v += dpp_f(v, 3);
;     const int x = __builtin_bit_cast(int, v);
;     return __builtin_bit_cast(float, __builtin_amdgcn_readlane(x, 0)) + __builtin_bit_cast(float, __builtin_amdgcn_readlane(x, 16))
;          + __builtin_bit_cast(float, __builtin_amdgcn_readlane(x, 32)) + __builtin_bit_cast(float, __builtin_amdgcn_readlane(x, 48));
; DI void phase1(const Params& p, unsigned char* smem) {
;     ...
;                 *(uint2*)(h1 + (size_t)row * 1024 + c) = pk4(o);
; #pragma unroll
;                 for (int e = 0; e < 4; ++e) {
;                     const float4 w0 = gw0[i * 4 + e], w1 = gw1[i * 4 + e];
;                     ga[0] += o[e] * w0.x; ga[1] += o[e] * w0.y; ga[2] += o[e] * w0.z; ga[3] += o[e] * w0.w;
;                     ga[4] += o[e] * w1.x; ga[5] += o[e] * w1.y; ga[6] += o[e] * w1.z; ga[7] += o[e] * w1.w;
;                 }
;             }
; #pragma unroll
;             for (int j = 0; j < 8; ++j) ga[j] = wsum(ga[j]);
	v_pk_fma_f32 v[200:201], v[200:201], v[242:243], v[214:215]
	s_nop 0
	v_fmac_f32_e32 v177, v96, v200
	v_pk_fma_f32 v[214:215], v[240:241], v[244:245], v[216:217]
	v_fmac_f32_e32 v177, v104, v201
	v_fmac_f32_e32 v177, v112, v214
	v_cvt_pk_bf16_f32 v216, v200, v201
	v_cvt_pk_bf16_f32 v217, v214, v215
	v_fmac_f32_e32 v177, v120, v215
	global_store_dwordx2 v[226:227], v[216:217], off offset:1536
	v_fma_f32 v216, v4, v220, 0
	v_fmac_f32_e32 v187, v97, v200
	v_add_f32_dpp v177, v177, v177 quad_perm:[1,0,3,2] row_mask:0xf bank_mask:0xf bound_ctrl:1
	v_fmac_f32_e32 v216, v12, v221
	v_fmac_f32_e32 v187, v105, v201
	v_add_f32_dpp v177, v177, v177 quad_perm:[2,3,0,1] row_mask:0xf bank_mask:0xf bound_ctrl:1
	v_fmac_f32_e32 v216, v20, v218
	v_fmac_f32_e32 v187, v113, v214
	v_add_f32_dpp v177, v177, v177 row_half_mirror row_mask:0xf bank_mask:0xf bound_ctrl:1
	v_fmac_f32_e32 v216, v28, v219
	v_fmac_f32_e32 v187, v121, v215
	v_add_f32_dpp v177, v177, v177 row_mirror row_mask:0xf bank_mask:0xf bound_ctrl:1
	v_fma_f32 v217, v5, v220, 0
	v_fmac_f32_e32 v216, v36, v228
	v_fmac_f32_e32 v189, v98, v200
	v_readlane_b32 s16, v177, 0
	v_readlane_b32 s31, v177, 16
	v_readlane_b32 s17, v177, 32
	v_readlane_b32 s30, v177, 48
	v_add_f32_dpp v177, v187, v187 quad_perm:[1,0,3,2] row_mask:0xf bank_mask:0xf bound_ctrl:1
	v_fmac_f32_e32 v217, v13, v221
	v_fmac_f32_e32 v216, v44, v229
	v_fmac_f32_e32 v189, v106, v201
	v_add_f32_dpp v177, v177, v177 quad_perm:[2,3,0,1] row_mask:0xf bank_mask:0xf bound_ctrl:1
	v_fmac_f32_e32 v217, v21, v218
	v_fmac_f32_e32 v216, v52, v222
	v_fmac_f32_e32 v189, v114, v214
	v_add_f32_dpp v177, v177, v177 row_half_mirror row_mask:0xf bank_mask:0xf bound_ctrl:1
	v_fmac_f32_e32 v217, v29, v219
	v_fmac_f32_e32 v216, v60, v223
	v_fmac_f32_e32 v189, v122, v215
	v_add_f32_dpp v177, v177, v177 row_mirror row_mask:0xf bank_mask:0xf bound_ctrl:1
	v_fmac_f32_e32 v217, v37, v228
	v_fmac_f32_e32 v216, v68, v238
	v_fmac_f32_e32 v191, v99, v200
	v_readlane_b32 s34, v177, 0
	v_readlane_b32 s42, v177, 16
	v_readlane_b32 s35, v177, 32
	v_readlane_b32 s41, v177, 48
	v_add_f32_dpp v177, v189, v189 quad_perm:[1,0,3,2] row_mask:0xf bank_mask:0xf bound_ctrl:1
	v_fmac_f32_e32 v217, v45, v229
	v_fmac_f32_e32 v216, v76, v239
	v_fmac_f32_e32 v191, v107, v201
	v_add_f32_dpp v177, v177, v177 quad_perm:[2,3,0,1] row_mask:0xf bank_mask:0xf bound_ctrl:1
	v_fmac_f32_e32 v217, v53, v222
	v_fmac_f32_e32 v216, v84, v210
	v_fmac_f32_e32 v191, v115, v214
	v_add_f32_dpp v177, v177, v177 row_half_mirror row_mask:0xf bank_mask:0xf bound_ctrl:1
	v_fmac_f32_e32 v217, v61, v223
	v_fmac_f32_e32 v216, v92, v211
	v_fmac_f32_e32 v191, v123, v215
	v_add_f32_dpp v177, v177, v177 row_mirror row_mask:0xf bank_mask:0xf bound_ctrl:1
	v_fma_f32 v220, v7, v220, 0
	v_fmac_f32_e32 v217, v69, v238
	v_fmac_f32_e32 v216, v100, v200
	v_readlane_b32 s43, v177, 0
	v_readlane_b32 s46, v177, 16
	v_readlane_b32 s44, v177, 32
	v_readlane_b32 s45, v177, 48
	v_add_f32_dpp v177, v191, v191 quad_perm:[1,0,3,2] row_mask:0xf bank_mask:0xf bound_ctrl:1
	v_fmac_f32_e32 v220, v15, v221
	v_fmac_f32_e32 v217, v77, v239
	v_fmac_f32_e32 v216, v108, v201
	v_add_f32_dpp v177, v177, v177 quad_perm:[2,3,0,1] row_mask:0xf bank_mask:0xf bound_ctrl:1
	v_fmac_f32_e32 v220, v23, v218
	v_fmac_f32_e32 v217, v85, v210
	v_fmac_f32_e32 v216, v116, v214
	v_add_f32_dpp v177, v177, v177 row_half_mirror row_mask:0xf bank_mask:0xf bound_ctrl:1
	v_fmac_f32_e32 v220, v31, v219
	v_fmac_f32_e32 v217, v93, v211
	v_fmac_f32_e32 v216, v124, v215
	v_add_f32_dpp v177, v177, v177 row_mirror row_mask:0xf bank_mask:0xf bound_ctrl:1
	v_fmac_f32_e32 v220, v39, v228
	v_fmac_f32_e32 v217, v101, v200
	v_readlane_b32 s47, v177, 0
	v_readlane_b32 s50, v177, 16
	v_readlane_b32 s48, v177, 32
	v_readlane_b32 s49, v177, 48
	v_add_f32_dpp v177, v216, v216 quad_perm:[1,0,3,2] row_mask:0xf bank_mask:0xf bound_ctrl:1
	v_fmac_f32_e32 v220, v47, v229
	v_fmac_f32_e32 v217, v109, v201
	v_add_f32_dpp v177, v177, v177 quad_perm:[2,3,0,1] row_mask:0xf bank_mask:0xf bound_ctrl:1
	v_fmac_f32_e32 v220, v55, v222
	v_fmac_f32_e32 v217, v117, v214
	v_add_f32_dpp v177, v177, v177 row_half_mirror row_mask:0xf bank_mask:0xf bound_ctrl:1
	v_fmac_f32_e32 v220, v63, v223
	v_fmac_f32_e32 v217, v125, v215
	v_add_f32_dpp v177, v177, v177 row_mirror row_mask:0xf bank_mask:0xf bound_ctrl:1
	v_fmac_f32_e32 v220, v71, v238
	v_fmac_f32_e32 v224, v102, v200
	v_readlane_b32 s51, v177, 0
	v_readlane_b32 s55, v177, 16
	v_readlane_b32 s52, v177, 32
	v_readlane_b32 s53, v177, 48
	v_add_f32_dpp v177, v217, v217 quad_perm:[1,0,3,2] row_mask:0xf bank_mask:0xf bound_ctrl:1
	v_fmac_f32_e32 v220, v79, v239
	v_fmac_f32_e32 v224, v110, v201
	v_add_f32_dpp v177, v177, v177 quad_perm:[2,3,0,1] row_mask:0xf bank_mask:0xf bound_ctrl:1
	v_fmac_f32_e32 v220, v87, v210
	v_fmac_f32_e32 v224, v118, v214
	v_add_f32_dpp v177, v177, v177 row_half_mirror row_mask:0xf bank_mask:0xf bound_ctrl:1
	v_fmac_f32_e32 v220, v95, v211
	v_fmac_f32_e32 v224, v126, v215
	v_add_f32_dpp v177, v177, v177 row_mirror row_mask:0xf bank_mask:0xf bound_ctrl:1
	v_fmac_f32_e32 v220, v103, v200
	v_readlane_b32 s56, v177, 0
	v_readlane_b32 s73, v177, 16
	v_readlane_b32 s57, v177, 32
	v_readlane_b32 s72, v177, 48
	v_add_f32_dpp v177, v224, v224 quad_perm:[1,0,3,2] row_mask:0xf bank_mask:0xf bound_ctrl:1
	v_fmac_f32_e32 v220, v111, v201
	v_fmac_f32_e32 v220, v119, v214
	v_add_f32_dpp v177, v177, v177 quad_perm:[2,3,0,1] row_mask:0xf bank_mask:0xf bound_ctrl:1
	v_fmac_f32_e32 v220, v127, v215
	s_nop 0
	v_add_f32_dpp v177, v177, v177 row_half_mirror row_mask:0xf bank_mask:0xf bound_ctrl:1
	s_nop 1
	v_add_f32_dpp v177, v177, v177 row_mirror row_mask:0xf bank_mask:0xf bound_ctrl:1
	s_nop 0
	v_readlane_b32 s74, v177, 0
	v_readlane_b32 s83, v177, 16
	v_readlane_b32 s75, v177, 32
	v_readlane_b32 s82, v177, 48
	v_add_f32_dpp v177, v220, v220 quad_perm:[1,0,3,2] row_mask:0xf bank_mask:0xf bound_ctrl:1
	s_nop 1
	v_add_f32_dpp v177, v177, v177 quad_perm:[2,3,0,1] row_mask:0xf bank_mask:0xf bound_ctrl:1
	s_nop 1
	v_add_f32_dpp v177, v177, v177 row_half_mirror row_mask:0xf bank_mask:0xf bound_ctrl:1
	s_nop 1
	v_add_f32_dpp v177, v177, v177 row_mirror row_mask:0xf bank_mask:0xf bound_ctrl:1
	s_nop 0
	v_readlane_b32 s84, v177, 0
	v_readlane_b32 s87, v177, 16
	v_readlane_b32 s85, v177, 32
	v_readlane_b32 s86, v177, 48
	v_lshlrev_b32_e32 v177, 2, v193
	v_add_u32_e32 v200, v231, v177
	v_add_u32_e32 v210, v177, v230
	v_ashrrev_i32_e32 v201, 31, v200
	v_ashrrev_i32_e32 v211, 31, v210
	v_lshlrev_b64 v[200:201], 15, v[200:201]
	v_lshlrev_b64 v[210:211], 15, v[210:211]
	v_lshl_add_u64 v[200:201], s[20:21], 0, v[200:201]
	v_lshl_add_u64 v[210:211], s[88:89], 0, v[210:211]
	s_and_saveexec_b64 s[28:29], vcc
	s_cbranch_execz .LBB0_197
; DI float logsig(float x) { return (x < 0.f) ? (x - log1pf(__expf(x))) : (-log1pf(__expf(-x))); }
; DI void phase1(const Params& p, unsigned char* smem) {
;     ...
;             if (lane < 8) {
;                 float val = ga[0];
; #pragma unroll
;                 for (int j = 1; j < 8; ++j) val = (lane == j) ? ga[j] : val;
;                 val += p.in[5][2048 + lane];
;                 const int b = row >> 13, sidx = row & 8191;
;                 if (lane < 4) ig[(size_t)(b * 4 + lane) * 8192 + sidx] = val;
;                 else lf[(size_t)(b * 4 + lane - 4) * 8192 + sidx] = logsig(val);
	v_mov_b32_e32 v215, s42
	v_mov_b32_e32 v216, s31
	v_mov_b32_e32 v214, s46
	v_add_f32_e32 v215, s34, v215
	v_add_f32_e32 v216, s16, v216
	v_mov_b32_e32 v193, s50
	v_add_f32_e32 v214, s43, v214
	v_add_f32_e32 v215, s35, v215
	v_add_f32_e32 v216, s17, v216
	v_mov_b32_e32 v191, s55
	v_add_f32_e32 v193, s47, v193
	v_add_f32_e32 v214, s44, v214
	v_add_f32_e32 v215, s41, v215
	v_add_f32_e32 v216, s30, v216
	v_mov_b32_e32 v189, s73
	v_add_f32_e32 v191, s51, v191
	v_add_f32_e32 v193, s48, v193
	v_add_f32_e32 v214, s45, v214
	v_cndmask_b32_e64 v215, v216, v215, s[0:1]
	v_mov_b32_e32 v187, s83
	v_add_f32_e32 v189, s56, v189
	v_add_f32_e32 v191, s52, v191
	v_add_f32_e32 v193, s49, v193
	v_cndmask_b32_e64 v214, v215, v214, s[14:15]
	v_mov_b32_e32 v177, s87
	v_add_f32_e32 v187, s74, v187
	v_add_f32_e32 v189, s57, v189
	v_add_f32_e32 v191, s53, v191
	v_cndmask_b32_e64 v193, v214, v193, s[4:5]
	v_add_f32_e32 v177, s84, v177
	v_add_f32_e32 v187, s75, v187
	v_add_f32_e32 v189, s72, v189
	v_cndmask_b32_e64 v191, v193, v191, s[6:7]
	v_add_f32_e32 v177, s85, v177
	v_add_f32_e32 v187, s82, v187
	v_cndmask_b32_e64 v189, v191, v189, s[8:9]
	v_add_f32_e32 v177, s86, v177
	v_cndmask_b32_e64 v187, v189, v187, s[10:11]
	v_cndmask_b32_e64 v177, v187, v177, s[12:13]
	v_mov_b32_e32 v187, v251
	v_mov_b64_e32 v[214:215], v[210:211]
	v_add_f32_e32 v177, v177, v187
	s_and_saveexec_b64 s[30:31], s[24:25]
	s_cbranch_execz .LBB0_196
	v_cmp_ngt_f32_e64 s[16:17], 0, v177
	s_and_saveexec_b64 s[34:35], s[16:17]
	s_xor_b64 s[34:35], exec, s[34:35]
	s_cbranch_execz .LBB0_193
	v_mul_f32_e32 v177, 0xbfb8aa3b, v177
	v_exp_f32_e32 v177, v177
	s_nop 0
	v_add_f32_e32 v187, 1.0, v177
	v_add_f32_e32 v189, -1.0, v187
	v_sub_f32_e32 v193, v189, v187
	v_frexp_mant_f32_e32 v191, v187
	v_cvt_f64_f32_e32 v[214:215], v187
	v_sub_f32_e32 v189, v177, v189
	v_add_f32_e32 v193, 1.0, v193
	v_add_f32_e32 v189, v189, v193
	v_frexp_exp_i32_f64_e32 v193, v[214:215]
	v_cmp_gt_f32_e64 s[16:17], s37, v191
	s_nop 1
	v_subbrev_co_u32_e64 v191, s[16:17], 0, v193, s[16:17]
	v_sub_u32_e32 v193, 0, v191
	v_ldexp_f32 v187, v187, v193
	v_ldexp_f32 v189, v189, v193
	v_add_f32_e32 v193, -1.0, v187
	v_add_f32_e32 v215, 1.0, v187
	v_add_f32_e32 v214, 1.0, v193
	v_add_f32_e32 v216, -1.0, v215
	v_sub_f32_e32 v214, v187, v214
	v_sub_f32_e32 v187, v187, v216
	v_add_f32_e32 v187, v189, v187
	v_add_f32_e32 v214, v189, v214
	v_add_f32_e32 v189, v215, v187
	v_rcp_f32_e32 v222, v189
	v_sub_f32_e32 v215, v189, v215
	v_sub_f32_e32 v187, v187, v215
	v_add_f32_e32 v215, v193, v214
	v_mul_f32_e32 v223, v215, v222
	v_mul_f32_e32 v216, v189, v223
	v_fma_f32 v218, v223, v189, -v216
	v_sub_f32_e32 v193, v215, v193
	v_fmac_f32_e32 v218, v223, v187
	v_sub_f32_e32 v193, v214, v193
	v_add_f32_e32 v214, v216, v218
	v_sub_f32_e32 v217, v215, v214
	v_pk_add_f32 v[220:221], v[214:215], v[216:217] neg_lo:[0,1] neg_hi:[0,1]
	v_mov_b32_e32 v219, v214
	v_pk_add_f32 v[214:215], v[220:221], v[218:219] neg_lo:[0,1] neg_hi:[0,1]
	v_cmp_neq_f32_e64 s[16:17], s39, v177
	v_add_f32_e32 v193, v193, v215
	v_add_f32_e32 v193, v214, v193
	v_add_f32_e32 v215, v217, v193
	v_mul_f32_e32 v224, v222, v215
	v_mul_f32_e32 v216, v189, v224
	v_fma_f32 v218, v224, v189, -v216
	v_fmac_f32_e32 v218, v224, v187
	v_add_f32_e32 v214, v216, v218
	v_sub_f32_e32 v187, v217, v215
	v_sub_f32_e32 v217, v215, v214
	v_pk_add_f32 v[220:221], v[214:215], v[216:217] neg_lo:[0,1] neg_hi:[0,1]
	v_mov_b32_e32 v219, v214
	v_add_f32_e32 v187, v193, v187
	v_pk_add_f32 v[214:215], v[220:221], v[218:219] neg_lo:[0,1] neg_hi:[0,1]
	v_add_f32_e32 v189, v223, v224
	v_add_f32_e32 v187, v187, v215
	v_add_f32_e32 v187, v214, v187
	v_add_f32_e32 v187, v217, v187
	v_sub_f32_e32 v193, v189, v223
	v_mul_f32_e32 v187, v222, v187
	v_sub_f32_e32 v193, v224, v193
	v_add_f32_e32 v187, v193, v187
	v_add_f32_e32 v215, v189, v187
	v_cvt_f32_i32_e32 v214, v191
	v_mul_f32_e32 v216, v215, v215
	v_fmamk_f32 v193, v216, 0x3e9b6dac, v233
	v_fmaak_f32 v193, v216, v193, 0x3f2aaada
	v_sub_f32_e32 v189, v215, v189
	v_ldexp_f32 v217, v215, 1
	v_mul_f32_e32 v215, v215, v216
	v_pk_mul_f32 v[218:219], v[214:215], v[192:193]
	v_sub_f32_e32 v187, v187, v189
	v_fma_f32 v216, v214, s38, -v218
	v_fmac_f32_e32 v216, 0xb102e308, v214
	v_pk_add_f32 v[214:215], v[218:219], v[216:217]
	v_ldexp_f32 v187, v187, 1
	v_sub_f32_e32 v189, v215, v217
	v_sub_f32_e32 v189, v219, v189
	v_add_f32_e32 v221, v187, v189
	v_mov_b32_e32 v220, v218
	v_pk_add_f32 v[218:219], v[214:215], v[218:219] neg_lo:[0,1] neg_hi:[0,1]
	v_pk_add_f32 v[222:223], v[214:215], v[220:221]
	v_mov_b32_e32 v217, v214
	v_mov_b32_e32 v219, v223
	v_pk_add_f32 v[226:227], v[216:217], v[218:219] neg_lo:[0,1] neg_hi:[0,1]
	v_pk_add_f32 v[216:217], v[216:217], v[218:219]
	v_mov_b32_e32 v220, v221
	v_pk_add_f32 v[218:219], v[216:217], v[214:215] op_sel:[1,0] op_sel_hi:[0,1] neg_lo:[0,1] neg_hi:[0,1]
	v_pk_add_f32 v[228:229], v[222:223], v[218:219] op_sel_hi:[1,0] neg_lo:[0,1] neg_hi:[0,1]
	v_mov_b32_e32 v222, v223
	v_mov_b32_e32 v223, v217
	v_pk_mov_b32 v[218:219], v[214:215], v[218:219] op_sel:[1,0]
	v_mov_b32_e32 v221, v214
	v_pk_add_f32 v[218:219], v[222:223], v[218:219] neg_lo:[0,1] neg_hi:[0,1]
	v_mov_b32_e32 v228, v226
	v_pk_add_f32 v[214:215], v[220:221], v[218:219] neg_lo:[0,1] neg_hi:[0,1]
	v_mov_b32_e32 v227, v217
	v_pk_add_f32 v[218:219], v[228:229], v[214:215]
	s_nop 0
	v_pk_add_f32 v[220:221], v[218:219], v[218:219] op_sel:[0,1] op_sel_hi:[1,0]
	s_nop 0
	v_pk_add_f32 v[216:217], v[216:217], v[220:221] op_sel:[1,0] op_sel_hi:[0,1]
	v_mov_b32_e32 v219, v216
	v_pk_add_f32 v[222:223], v[218:219], v[226:227] neg_lo:[0,1] neg_hi:[0,1]
	v_mov_b32_e32 v215, v220
	v_sub_f32_e32 v187, v218, v222
	v_pk_add_f32 v[214:215], v[214:215], v[222:223] neg_lo:[0,1] neg_hi:[0,1]
	v_sub_f32_e32 v187, v226, v187
	v_add_f32_e32 v187, v214, v187
	v_add_f32_e32 v187, v187, v215
	v_add_f32_e32 v187, v216, v187
	v_cndmask_b32_e64 v187, v234, v187, s[16:17]
	v_cmp_ngt_f32_e64 s[16:17], -1.0, v177
	s_nop 1
	v_cndmask_b32_e64 v187, v235, v187, s[16:17]
	v_cmp_neq_f32_e64 s[16:17], -1.0, v177
	s_nop 1
	v_cndmask_b32_e64 v187, v236, v187, s[16:17]
	v_cmp_lt_f32_e64 s[16:17], |v177|, s40
	s_nop 1
	v_cndmask_b32_e64 v177, v187, v177, s[16:17]
	v_xor_b32_e32 v177, 0x80000000, v177

; DI uint2 pk4(f32x4 v) { return make_uint2(pk2(v[0], v[1]), pk2(v[2], v[3])); }
; DI void row_stats(const float (&v)[16], float& mean, float& rstd) {
;     float s = 0.f;
; #pragma unroll
;     for (int i = 0; i < 16; ++i) s += v[i];
;     mean = wsum(s) * (1.f / 1024.f);
;     float q = 0.f;
; #pragma unroll
;     for (int i = 0; i < 16; ++i) { float d = v[i] - mean; q += d * d; }
;     rstd = rsqrtf(wsum(q) * (1.f / 1024.f) + 1e-5f);
; }
; DI void phase1(const Params& p, unsigned char* smem) {
;     ...
;         for (int rr = 0; rr < 4; ++rr) {
;             const int row = row0 + rr;
;             float mean, rstd; row_stats(vv[rr], mean, rstd);
;             const float* mb = mod + (row >> 13) * 6144;
;             float ga[8];
; #pragma unroll
;             for (int j = 0; j < 8; ++j) ga[j] = 0.f;
; #pragma unroll
;             for (int i = 0; i < 4; ++i) {
;                 int c = i * 256 + lane * 4;
;                 float4 sh = *(const float4*)(mb + c), sc = *(const float4*)(mb + 1024 + c);
;                 f32x4 o;
;                 o[0] = (vv[rr][4 * i] - mean) * rstd * (1.f + sc.x) + sh.x;
;                 o[1] = (vv[rr][4 * i + 1] - mean) * rstd * (1.f + sc.y) + sh.y;
;                 o[2] = (vv[rr][4 * i + 2] - mean) * rstd * (1.f + sc.z) + sh.z;
;                 o[3] = (vv[rr][4 * i + 3] - mean) * rstd * (1.f + sc.w) + sh.w;
;                 *(uint2*)(h1 + (size_t)row * 1024 + c) = pk4(o);
.LBB0_197:
	s_or_b64 exec, exec, s[28:29]
	ds_read_b128 v[214:217], v237 offset:5120
	ds_read_b128 v[218:221], v237 offset:1024
	s_waitcnt vmcnt(12)
	v_add_f32_e32 v177, 0, v172
	v_add_f32_e32 v177, v177, v173
	v_add_f32_e32 v177, v177, v174
	v_add_f32_e32 v177, v177, v175
	v_add_f32_e32 v177, v177, v168
	v_add_f32_e32 v177, v177, v169
	v_add_f32_e32 v177, v177, v170
	v_add_f32_e32 v177, v177, v171
	v_add_f32_e32 v177, v177, v164
	v_add_f32_e32 v177, v177, v165
	v_add_f32_e32 v177, v177, v166
	v_add_f32_e32 v177, v177, v167
	v_add_f32_e32 v177, v177, v160
	v_add_f32_e32 v177, v177, v161
	v_add_f32_e32 v177, v177, v162
	v_add_f32_e32 v177, v177, v163
	v_lshlrev_b64 v[222:223], 11, v[212:213]
	s_nop 0
	v_add_f32_dpp v177, v177, v177 quad_perm:[1,0,3,2] row_mask:0xf bank_mask:0xf bound_ctrl:1
	s_nop 1
	v_add_f32_dpp v177, v177, v177 quad_perm:[2,3,0,1] row_mask:0xf bank_mask:0xf bound_ctrl:1
	s_nop 1
	v_add_f32_dpp v177, v177, v177 row_half_mirror row_mask:0xf bank_mask:0xf bound_ctrl:1
	s_nop 1
	v_add_f32_dpp v177, v177, v177 row_mirror row_mask:0xf bank_mask:0xf bound_ctrl:1
	s_nop 0
	v_readlane_b32 s17, v177, 16
	v_readlane_b32 s16, v177, 0
	v_readlane_b32 s18, v177, 32
	v_readlane_b32 s19, v177, 48
	v_mov_b32_e32 v177, s17
	v_add_f32_e32 v177, s16, v177
	v_add_f32_e32 v177, s18, v177
	v_add_f32_e32 v177, s19, v177
	v_mul_f32_e32 v224, 0x3a800000, v177
	v_pk_add_f32 v[172:173], v[172:173], v[224:225] op_sel_hi:[1,0] neg_lo:[0,1] neg_hi:[0,1]
	v_pk_add_f32 v[174:175], v[174:175], v[224:225] op_sel_hi:[1,0] neg_lo:[0,1] neg_hi:[0,1]
	v_pk_add_f32 v[240:241], v[164:165], v[224:225] op_sel_hi:[1,0] neg_lo:[0,1] neg_hi:[0,1]
	v_pk_add_f32 v[164:165], v[162:163], v[224:225] op_sel_hi:[1,0] neg_lo:[0,1] neg_hi:[0,1]
	v_pk_mul_f32 v[162:163], v[172:173], v[172:173]
	v_pk_add_f32 v[238:239], v[166:167], v[224:225] op_sel_hi:[1,0] neg_lo:[0,1] neg_hi:[0,1]
	v_pk_add_f32 v[166:167], v[160:161], v[224:225] op_sel_hi:[1,0] neg_lo:[0,1] neg_hi:[0,1]
	v_pk_mul_f32 v[160:161], v[174:175], v[174:175]
	v_add_f32_e32 v162, v162, v163
	v_pk_add_f32 v[228:229], v[168:169], v[224:225] op_sel_hi:[1,0] neg_lo:[0,1] neg_hi:[0,1]
	v_add_f32_e32 v160, v160, v162
	v_pk_add_f32 v[226:227], v[170:171], v[224:225] op_sel_hi:[1,0] neg_lo:[0,1] neg_hi:[0,1]
	v_pk_mul_f32 v[170:171], v[228:229], v[228:229]
	v_add_f32_e32 v160, v161, v160
	v_add_f32_e32 v160, v170, v160
	v_pk_mul_f32 v[168:169], v[226:227], v[226:227]
	v_add_f32_e32 v160, v171, v160
	v_add_f32_e32 v160, v168, v160
	v_pk_mul_f32 v[244:245], v[240:241], v[240:241]
	v_add_f32_e32 v160, v169, v160
	v_add_f32_e32 v160, v244, v160
	v_pk_mul_f32 v[242:243], v[238:239], v[238:239]
	v_add_f32_e32 v160, v245, v160
	v_add_f32_e32 v160, v242, v160
	v_pk_mul_f32 v[248:249], v[166:167], v[166:167]
	v_add_f32_e32 v160, v243, v160
	v_add_f32_e32 v160, v248, v160
	v_pk_mul_f32 v[246:247], v[164:165], v[164:165]
	v_add_f32_e32 v160, v249, v160
	v_add_f32_e32 v160, v246, v160
	v_add_f32_e32 v160, v247, v160
	s_waitcnt lgkmcnt(1)
	v_pk_add_f32 v[162:163], v[214:215], 1.0 op_sel_hi:[1,0]
	v_add_f32_dpp v160, v160, v160 quad_perm:[1,0,3,2] row_mask:0xf bank_mask:0xf bound_ctrl:1
	v_pk_add_f32 v[170:171], v[216:217], 1.0 op_sel_hi:[1,0]
	s_nop 0
	v_add_f32_dpp v160, v160, v160 quad_perm:[2,3,0,1] row_mask:0xf bank_mask:0xf bound_ctrl:1
	s_nop 1
	v_add_f32_dpp v160, v160, v160 row_half_mirror row_mask:0xf bank_mask:0xf bound_ctrl:1
	s_nop 1
	v_add_f32_dpp v160, v160, v160 row_mirror row_mask:0xf bank_mask:0xf bound_ctrl:1
	s_nop 0
	v_readlane_b32 s17, v160, 16
	v_readlane_b32 s16, v160, 0
	v_readlane_b32 s18, v160, 32
	v_readlane_b32 s19, v160, 48
	v_mov_b32_e32 v160, s17
	v_add_f32_e32 v160, s16, v160
	v_add_f32_e32 v160, s18, v160
	v_add_f32_e32 v160, s19, v160
	v_fmamk_f32 v160, v160, 0x3a800000, v232
	v_mul_f32_e32 v161, 0x4b800000, v160
	v_cmp_gt_f32_e64 s[16:17], s36, v160
	s_nop 1
	v_cndmask_b32_e64 v160, v160, v161, s[16:17]
	v_rsq_f32_e32 v168, v160
	v_lshl_add_u64 v[160:161], v[184:185], 0, v[222:223]
	v_mul_f32_e32 v169, 0x45800000, v168
	v_cndmask_b32_e64 v222, v168, v169, s[16:17]
	v_pk_mul_f32 v[168:169], v[172:173], v[222:223] op_sel_hi:[1,0]
	s_waitcnt lgkmcnt(0)
	v_pk_fma_f32 v[168:169], v[162:163], v[168:169], v[218:219]
	v_pk_mul_f32 v[162:163], v[174:175], v[222:223] op_sel_hi:[1,0]
	v_pk_mul_f32 v[174:175], v[228:229], v[222:223] op_sel_hi:[1,0]
	v_pk_fma_f32 v[162:163], v[170:171], v[162:163], v[220:221]
	v_cvt_pk_bf16_f32 v170, v168, v169
	v_cvt_pk_bf16_f32 v171, v162, v163
	global_store_dwordx2 v[160:161], v[170:171], off
	ds_read_b128 v[170:173], v237 offset:6144
	s_nop 0
	ds_read_b128 v[214:217], v237 offset:2048
	v_pk_mul_f32 v[218:219], v[226:227], v[222:223] op_sel_hi:[1,0]
	v_pk_mul_f32 v[220:221], v[240:241], v[222:223] op_sel_hi:[1,0]
	v_pk_mul_f32 v[226:227], v[238:239], v[222:223] op_sel_hi:[1,0]
	v_pk_mul_f32 v[228:229], v[166:167], v[222:223] op_sel_hi:[1,0]
	v_pk_mul_f32 v[222:223], v[164:165], v[222:223] op_sel_hi:[1,0]
	v_fma_f32 v177, v0, v168, 0
	v_fma_f32 v187, v1, v168, 0
	v_fma_f32 v189, v2, v168, 0
	v_fma_f32 v191, v3, v168, 0
	v_fma_f32 v193, v4, v168, 0
	v_fma_f32 v213, v5, v168, 0
	v_fma_f32 v224, v6, v168, 0
	v_fma_f32 v225, v7, v168, 0
	v_fmac_f32_e32 v177, v8, v169
	v_fmac_f32_e32 v187, v9, v169
	v_fmac_f32_e32 v189, v10, v169
	v_fmac_f32_e32 v191, v11, v169
	v_fmac_f32_e32 v193, v12, v169
	v_fmac_f32_e32 v213, v13, v169
	v_fmac_f32_e32 v224, v14, v169
	v_fmac_f32_e32 v225, v15, v169
	v_fmac_f32_e32 v177, v16, v162
	v_fmac_f32_e32 v187, v17, v162
	v_fmac_f32_e32 v189, v18, v162
	v_fmac_f32_e32 v191, v19, v162
	v_fmac_f32_e32 v193, v20, v162
	v_fmac_f32_e32 v213, v21, v162
	v_fmac_f32_e32 v224, v22, v162
	v_fmac_f32_e32 v225, v23, v162
	v_fmac_f32_e32 v177, v24, v163
	v_fmac_f32_e32 v187, v25, v163
	v_fmac_f32_e32 v189, v26, v163
	v_fmac_f32_e32 v191, v27, v163
	v_fmac_f32_e32 v193, v28, v163
	v_fmac_f32_e32 v213, v29, v163
	v_fmac_f32_e32 v224, v30, v163
	v_fmac_f32_e32 v225, v31, v163
	s_waitcnt lgkmcnt(1)
; DI uint2 pk4(f32x4 v) { return make_uint2(pk2(v[0], v[1]), pk2(v[2], v[3])); }
; DI void phase1(const Params& p, unsigned char* smem) {
;     ...
;             for (int i = 0; i < 4; ++i) {
;                 int c = i * 256 + lane * 4;
;                 float4 sh = *(const float4*)(mb + c), sc = *(const float4*)(mb + 1024 + c);
;                 f32x4 o;
;                 o[0] = (vv[rr][4 * i] - mean) * rstd * (1.f + sc.x) + sh.x;
;                 o[1] = (vv[rr][4 * i + 1] - mean) * rstd * (1.f + sc.y) + sh.y;
;                 o[2] = (vv[rr][4 * i + 2] - mean) * rstd * (1.f + sc.z) + sh.z;
;                 o[3] = (vv[rr][4 * i + 3] - mean) * rstd * (1.f + sc.w) + sh.w;
;                 *(uint2*)(h1 + (size_t)row * 1024 + c) = pk4(o);
; #pragma unroll
;                 for (int e = 0; e < 4; ++e) {
;                     const float4 w0 = gw0[i * 4 + e], w1 = gw1[i * 4 + e];
;                     ga[0] += o[e] * w0.x; ga[1] += o[e] * w0.y; ga[2] += o[e] * w0.z; ga[3] += o[e] * w0.w;
;                     ga[4] += o[e] * w1.x; ga[5] += o[e] * w1.y; ga[6] += o[e] * w1.z; ga[7] += o[e] * w1.w;
;                 }
	v_pk_add_f32 v[170:171], v[170:171], 1.0 op_sel_hi:[1,0]
	v_pk_add_f32 v[172:173], v[172:173], 1.0 op_sel_hi:[1,0]
	s_waitcnt lgkmcnt(0)
	v_pk_fma_f32 v[174:175], v[174:175], v[170:171], v[214:215]
	v_pk_fma_f32 v[218:219], v[218:219], v[172:173], v[216:217]
	v_cvt_pk_bf16_f32 v170, v174, v175
	v_cvt_pk_bf16_f32 v171, v218, v219
	global_store_dwordx2 v[160:161], v[170:171], off offset:512
	ds_read_b128 v[170:173], v237 offset:7168
	s_nop 0
	ds_read_b128 v[214:217], v237 offset:3072
	v_fmac_f32_e32 v177, v32, v174
	v_fmac_f32_e32 v187, v33, v174
	v_fmac_f32_e32 v189, v34, v174
	v_fmac_f32_e32 v191, v35, v174
	v_fmac_f32_e32 v193, v36, v174
	v_fmac_f32_e32 v213, v37, v174
	v_fmac_f32_e32 v224, v38, v174
	v_fmac_f32_e32 v225, v39, v174
	v_fmac_f32_e32 v177, v40, v175
	v_fmac_f32_e32 v187, v41, v175
	v_fmac_f32_e32 v189, v42, v175
	v_fmac_f32_e32 v191, v43, v175
	v_fmac_f32_e32 v193, v44, v175
	v_fmac_f32_e32 v213, v45, v175
	v_fmac_f32_e32 v224, v46, v175
	v_fmac_f32_e32 v225, v47, v175
	v_fmac_f32_e32 v177, v48, v218
	v_fmac_f32_e32 v187, v49, v218
	v_fmac_f32_e32 v189, v50, v218
	v_fmac_f32_e32 v191, v51, v218
	v_fmac_f32_e32 v193, v52, v218
	v_fmac_f32_e32 v213, v53, v218
	v_fmac_f32_e32 v224, v54, v218
	v_fmac_f32_e32 v225, v55, v218
	v_fmac_f32_e32 v177, v56, v219
	v_fmac_f32_e32 v187, v57, v219
	v_fmac_f32_e32 v189, v58, v219
	v_fmac_f32_e32 v191, v59, v219
	v_fmac_f32_e32 v193, v60, v219
	v_fmac_f32_e32 v213, v61, v219
	v_fmac_f32_e32 v224, v62, v219
	v_fmac_f32_e32 v225, v63, v219
	s_waitcnt lgkmcnt(1)
	v_pk_add_f32 v[164:165], v[170:171], 1.0 op_sel_hi:[1,0]
	v_pk_add_f32 v[166:167], v[172:173], 1.0 op_sel_hi:[1,0]
	s_waitcnt lgkmcnt(0)
	v_pk_fma_f32 v[172:173], v[220:221], v[164:165], v[214:215]
	v_pk_fma_f32 v[214:215], v[226:227], v[166:167], v[216:217]
	v_cvt_pk_bf16_f32 v164, v172, v173
	v_cvt_pk_bf16_f32 v165, v214, v215
	global_store_dwordx2 v[160:161], v[164:165], off offset:1024
	ds_read_b128 v[164:167], v237 offset:4096
	s_nop 0
	ds_read_b128 v[168:171], v237 offset:8192
	v_fmac_f32_e32 v177, v64, v172
	v_fmac_f32_e32 v187, v65, v172
	v_fmac_f32_e32 v189, v66, v172
	v_fmac_f32_e32 v191, v67, v172
	v_fmac_f32_e32 v193, v68, v172
	v_fmac_f32_e32 v213, v69, v172
	v_fmac_f32_e32 v224, v70, v172
	v_fmac_f32_e32 v225, v71, v172
	v_fmac_f32_e32 v177, v72, v173
	v_fmac_f32_e32 v187, v73, v173
	v_fmac_f32_e32 v189, v74, v173
	v_fmac_f32_e32 v191, v75, v173
	v_fmac_f32_e32 v193, v76, v173
	v_fmac_f32_e32 v213, v77, v173
	v_fmac_f32_e32 v224, v78, v173
	v_fmac_f32_e32 v225, v79, v173
	v_fmac_f32_e32 v177, v80, v214
	v_fmac_f32_e32 v187, v81, v214
	v_fmac_f32_e32 v189, v82, v214
	v_fmac_f32_e32 v191, v83, v214
	v_fmac_f32_e32 v193, v84, v214
	v_fmac_f32_e32 v213, v85, v214
	v_fmac_f32_e32 v224, v86, v214
	v_fmac_f32_e32 v225, v87, v214
	v_fmac_f32_e32 v177, v88, v215
	v_fmac_f32_e32 v187, v89, v215
	v_fmac_f32_e32 v189, v90, v215
	v_fmac_f32_e32 v191, v91, v215
	v_fmac_f32_e32 v193, v92, v215
	v_fmac_f32_e32 v213, v93, v215
	v_fmac_f32_e32 v224, v94, v215
	v_fmac_f32_e32 v225, v95, v215
	s_waitcnt lgkmcnt(0)
	v_pk_add_f32 v[162:163], v[168:169], 1.0 op_sel_hi:[1,0]
	s_nop 0
	v_pk_fma_f32 v[162:163], v[228:229], v[162:163], v[164:165]
	v_pk_add_f32 v[168:169], v[170:171], 1.0 op_sel_hi:[1,0]
	v_fmac_f32_e32 v177, v96, v162
	v_fmac_f32_e32 v187, v97, v162
	v_fmac_f32_e32 v189, v98, v162
	v_fmac_f32_e32 v191, v99, v162
	v_fmac_f32_e32 v193, v100, v162
	v_fmac_f32_e32 v213, v101, v162
	v_fmac_f32_e32 v224, v102, v162
	v_fmac_f32_e32 v225, v103, v162
	v_pk_fma_f32 v[164:165], v[222:223], v[168:169], v[166:167]
	v_fmac_f32_e32 v177, v104, v163
	v_fmac_f32_e32 v187, v105, v163
	v_fmac_f32_e32 v189, v106, v163
	v_fmac_f32_e32 v191, v107, v163
	v_fmac_f32_e32 v193, v108, v163
	v_fmac_f32_e32 v213, v109, v163
	v_fmac_f32_e32 v224, v110, v163
	v_fmac_f32_e32 v225, v111, v163
	v_fmac_f32_e32 v177, v112, v164
	v_fmac_f32_e32 v187, v113, v164
	v_fmac_f32_e32 v189, v114, v164
	v_fmac_f32_e32 v191, v115, v164
	v_fmac_f32_e32 v193, v116, v164
	v_fmac_f32_e32 v213, v117, v164
	v_fmac_f32_e32 v224, v118, v164
	v_fmac_f32_e32 v225, v119, v164
	v_cvt_pk_bf16_f32 v166, v162, v163
	v_cvt_pk_bf16_f32 v167, v164, v165
	v_fmac_f32_e32 v177, v120, v165
	v_fmac_f32_e32 v187, v121, v165
	v_fmac_f32_e32 v189, v122, v165
	v_fmac_f32_e32 v191, v123, v165
	v_fmac_f32_e32 v193, v124, v165
	v_fmac_f32_e32 v213, v125, v165
	v_fmac_f32_e32 v224, v126, v165
	v_fmac_f32_e32 v225, v127, v165
	global_store_dwordx2 v[160:161], v[166:167], off offset:1536
	v_add_f32_dpp v160, v177, v177 quad_perm:[1,0,3,2] row_mask:0xf bank_mask:0xf bound_ctrl:1
	v_add_f32_dpp v161, v187, v187 quad_perm:[1,0,3,2] row_mask:0xf bank_mask:0xf bound_ctrl:1
	v_add_f32_dpp v162, v189, v189 quad_perm:[1,0,3,2] row_mask:0xf bank_mask:0xf bound_ctrl:1
	v_add_f32_dpp v163, v191, v191 quad_perm:[1,0,3,2] row_mask:0xf bank_mask:0xf bound_ctrl:1
	v_add_f32_dpp v164, v193, v193 quad_perm:[1,0,3,2] row_mask:0xf bank_mask:0xf bound_ctrl:1
	v_add_f32_dpp v165, v213, v213 quad_perm:[1,0,3,2] row_mask:0xf bank_mask:0xf bound_ctrl:1
	v_add_f32_dpp v166, v224, v224 quad_perm:[1,0,3,2] row_mask:0xf bank_mask:0xf bound_ctrl:1
	v_add_f32_dpp v167, v225, v225 quad_perm:[1,0,3,2] row_mask:0xf bank_mask:0xf bound_ctrl:1
	v_add_f32_dpp v160, v160, v160 quad_perm:[2,3,0,1] row_mask:0xf bank_mask:0xf bound_ctrl:1
	v_add_f32_dpp v161, v161, v161 quad_perm:[2,3,0,1] row_mask:0xf bank_mask:0xf bound_ctrl:1
	v_add_f32_dpp v162, v162, v162 quad_perm:[2,3,0,1] row_mask:0xf bank_mask:0xf bound_ctrl:1
	v_add_f32_dpp v163, v163, v163 quad_perm:[2,3,0,1] row_mask:0xf bank_mask:0xf bound_ctrl:1
; DI void phase1(const Params& p, unsigned char* smem) {
;     ...
;             for (int j = 0; j < 8; ++j) ga[j] = wsum(ga[j]);
;             if (lane < 8) {
;                 float val = ga[0];
; #pragma unroll
;                 for (int j = 1; j < 8; ++j) val = (lane == j) ? ga[j] : val;
;                 val += p.in[5][2048 + lane];
;                 const int b = row >> 13, sidx = row & 8191;
;                 if (lane < 4) ig[(size_t)(b * 4 + lane) * 8192 + sidx] = val;
	v_add_f32_dpp v164, v164, v164 quad_perm:[2,3,0,1] row_mask:0xf bank_mask:0xf bound_ctrl:1
	v_add_f32_dpp v165, v165, v165 quad_perm:[2,3,0,1] row_mask:0xf bank_mask:0xf bound_ctrl:1
	v_add_f32_dpp v166, v166, v166 quad_perm:[2,3,0,1] row_mask:0xf bank_mask:0xf bound_ctrl:1
	v_add_f32_dpp v167, v167, v167 quad_perm:[2,3,0,1] row_mask:0xf bank_mask:0xf bound_ctrl:1
	v_add_f32_dpp v160, v160, v160 row_half_mirror row_mask:0xf bank_mask:0xf bound_ctrl:1
	v_add_f32_dpp v161, v161, v161 row_half_mirror row_mask:0xf bank_mask:0xf bound_ctrl:1
	v_add_f32_dpp v162, v162, v162 row_half_mirror row_mask:0xf bank_mask:0xf bound_ctrl:1
	v_add_f32_dpp v163, v163, v163 row_half_mirror row_mask:0xf bank_mask:0xf bound_ctrl:1
	v_add_f32_dpp v164, v164, v164 row_half_mirror row_mask:0xf bank_mask:0xf bound_ctrl:1
	v_add_f32_dpp v165, v165, v165 row_half_mirror row_mask:0xf bank_mask:0xf bound_ctrl:1
	v_add_f32_dpp v166, v166, v166 row_half_mirror row_mask:0xf bank_mask:0xf bound_ctrl:1
	v_add_f32_dpp v167, v167, v167 row_half_mirror row_mask:0xf bank_mask:0xf bound_ctrl:1
	v_add_f32_dpp v160, v160, v160 row_mirror row_mask:0xf bank_mask:0xf bound_ctrl:1
	v_add_f32_dpp v161, v161, v161 row_mirror row_mask:0xf bank_mask:0xf bound_ctrl:1
	v_add_f32_dpp v162, v162, v162 row_mirror row_mask:0xf bank_mask:0xf bound_ctrl:1
	v_add_f32_dpp v163, v163, v163 row_mirror row_mask:0xf bank_mask:0xf bound_ctrl:1
	v_add_f32_dpp v164, v164, v164 row_mirror row_mask:0xf bank_mask:0xf bound_ctrl:1
	v_add_f32_dpp v165, v165, v165 row_mirror row_mask:0xf bank_mask:0xf bound_ctrl:1
	v_add_f32_dpp v166, v166, v166 row_mirror row_mask:0xf bank_mask:0xf bound_ctrl:1
	v_add_f32_dpp v167, v167, v167 row_mirror row_mask:0xf bank_mask:0xf bound_ctrl:1
	v_readlane_b32 s16, v160, 0
	v_readlane_b32 s31, v160, 16
	v_readlane_b32 s17, v160, 32
	v_readlane_b32 s30, v160, 48
	v_readlane_b32 s34, v161, 0
	v_readlane_b32 s42, v161, 16
	v_readlane_b32 s35, v161, 32
	v_readlane_b32 s41, v161, 48
	v_readlane_b32 s43, v162, 0
	v_readlane_b32 s46, v162, 16
	v_readlane_b32 s44, v162, 32
	v_readlane_b32 s45, v162, 48
	v_readlane_b32 s47, v163, 0
	v_readlane_b32 s50, v163, 16
	v_readlane_b32 s48, v163, 32
	v_readlane_b32 s49, v163, 48
	v_readlane_b32 s51, v164, 0
	v_readlane_b32 s55, v164, 16
	v_readlane_b32 s52, v164, 32
	v_readlane_b32 s53, v164, 48
	v_readlane_b32 s56, v165, 0
	v_readlane_b32 s73, v165, 16
	v_readlane_b32 s57, v165, 32
	v_readlane_b32 s72, v165, 48
	v_readlane_b32 s74, v166, 0
	v_readlane_b32 s83, v166, 16
	v_readlane_b32 s75, v166, 32
	v_readlane_b32 s82, v166, 48
	v_readlane_b32 s84, v167, 0
	v_readlane_b32 s87, v167, 16
	v_readlane_b32 s85, v167, 32
	v_readlane_b32 s86, v167, 48
	s_and_saveexec_b64 s[28:29], vcc
	s_cbranch_execz .LBB0_205
	v_mov_b32_e32 v166, s42
	v_mov_b32_e32 v167, s31
	v_mov_b32_e32 v165, s46
	v_add_f32_e32 v166, s34, v166
	v_add_f32_e32 v167, s16, v167
	v_mov_b32_e32 v164, s50
	v_add_f32_e32 v165, s43, v165
	v_add_f32_e32 v166, s35, v166
	v_add_f32_e32 v167, s17, v167
	v_mov_b32_e32 v163, s55
	v_add_f32_e32 v164, s47, v164
	v_add_f32_e32 v165, s44, v165
	v_add_f32_e32 v166, s41, v166
	v_add_f32_e32 v167, s30, v167
	v_mov_b32_e32 v162, s73
	v_add_f32_e32 v163, s51, v163
	v_add_f32_e32 v164, s48, v164
	v_add_f32_e32 v165, s45, v165
	v_cndmask_b32_e64 v166, v167, v166, s[0:1]
	v_mov_b32_e32 v161, s83
	v_add_f32_e32 v162, s56, v162
	v_add_f32_e32 v163, s52, v163
	v_add_f32_e32 v164, s49, v164
	v_cndmask_b32_e64 v165, v166, v165, s[14:15]
	v_mov_b32_e32 v160, s87
	v_add_f32_e32 v161, s74, v161
	v_add_f32_e32 v162, s57, v162
	v_add_f32_e32 v163, s53, v163
	v_cndmask_b32_e64 v164, v165, v164, s[4:5]
	v_add_f32_e32 v160, s84, v160
	v_add_f32_e32 v161, s75, v161
	v_add_f32_e32 v162, s72, v162
	v_cndmask_b32_e64 v163, v164, v163, s[6:7]
	v_add_f32_e32 v160, s85, v160
	v_add_f32_e32 v161, s82, v161
	v_cndmask_b32_e64 v162, v163, v162, s[8:9]
	v_add_f32_e32 v160, s86, v160
	v_cndmask_b32_e64 v161, v162, v161, s[10:11]
	v_cndmask_b32_e64 v160, v161, v160, s[12:13]
	v_mov_b32_e32 v161, v251
	v_add_f32_e32 v162, v160, v161
	v_mov_b64_e32 v[160:161], v[210:211]
	s_and_saveexec_b64 s[30:31], s[24:25]
	s_cbranch_execz .LBB0_204
	v_cmp_ngt_f32_e64 s[16:17], 0, v162
	s_and_saveexec_b64 s[34:35], s[16:17]
	s_xor_b64 s[34:35], exec, s[34:35]
	s_cbranch_execz .LBB0_201
; DI float logsig(float x) { return (x < 0.f) ? (x - log1pf(__expf(x))) : (-log1pf(__expf(-x))); }
; DI void phase1(const Params& p, unsigned char* smem) {
;     ...
;                 else lf[(size_t)(b * 4 + lane - 4) * 8192 + sidx] = logsig(val);
	v_mul_f32_e32 v160, 0xbfb8aa3b, v162
	v_exp_f32_e32 v174, v160
	s_nop 0
	v_add_f32_e32 v162, 1.0, v174
	v_frexp_mant_f32_e32 v164, v162
	v_cvt_f64_f32_e32 v[160:161], v162
	v_frexp_exp_i32_f64_e32 v160, v[160:161]
	v_cmp_gt_f32_e64 s[16:17], s37, v164
	v_add_f32_e32 v163, -1.0, v162
	v_sub_f32_e32 v165, v163, v162
	v_subbrev_co_u32_e64 v168, s[16:17], 0, v160, s[16:17]
	v_sub_u32_e32 v160, 0, v168
	v_sub_f32_e32 v163, v174, v163
	v_add_f32_e32 v165, 1.0, v165
	v_ldexp_f32 v161, v162, v160
	v_add_f32_e32 v163, v163, v165
	v_add_f32_e32 v162, -1.0, v161
	v_add_f32_e32 v164, 1.0, v161
	v_ldexp_f32 v160, v163, v160
	v_add_f32_e32 v163, 1.0, v162
	v_add_f32_e32 v165, -1.0, v164
	v_sub_f32_e32 v163, v161, v163
	v_sub_f32_e32 v161, v161, v165
	v_add_f32_e32 v163, v160, v163
	v_add_f32_e32 v160, v160, v161
	v_add_f32_e32 v169, v164, v160
	v_rcp_f32_e32 v171, v169
	v_sub_f32_e32 v161, v169, v164
	v_sub_f32_e32 v170, v160, v161
	v_add_f32_e32 v161, v162, v163
	v_mul_f32_e32 v173, v161, v171
	v_sub_f32_e32 v160, v161, v162
	v_mul_f32_e32 v162, v169, v173
	v_fma_f32 v164, v173, v169, -v162
	v_fmac_f32_e32 v164, v173, v170
	v_sub_f32_e32 v172, v163, v160
	v_add_f32_e32 v160, v162, v164
	v_sub_f32_e32 v163, v161, v160
	v_pk_add_f32 v[166:167], v[160:161], v[162:163] neg_lo:[0,1] neg_hi:[0,1]
	v_mov_b32_e32 v165, v160
	v_pk_add_f32 v[160:161], v[166:167], v[164:165] neg_lo:[0,1] neg_hi:[0,1]
	v_cmp_neq_f32_e64 s[16:17], s39, v174
	v_add_f32_e32 v161, v172, v161
	v_add_f32_e32 v160, v160, v161
	v_add_f32_e32 v161, v163, v160
	v_mul_f32_e32 v172, v171, v161
	v_mul_f32_e32 v162, v169, v172
	v_fma_f32 v164, v172, v169, -v162
	v_fmac_f32_e32 v164, v172, v170
	v_sub_f32_e32 v163, v163, v161
	v_add_f32_e32 v169, v160, v163
	v_add_f32_e32 v160, v162, v164
	v_sub_f32_e32 v163, v161, v160
	v_pk_add_f32 v[166:167], v[160:161], v[162:163] neg_lo:[0,1] neg_hi:[0,1]
	v_mov_b32_e32 v165, v160
	v_pk_add_f32 v[160:161], v[166:167], v[164:165] neg_lo:[0,1] neg_hi:[0,1]
	s_nop 0
	v_add_f32_e32 v161, v169, v161
	v_add_f32_e32 v160, v160, v161
	v_add_f32_e32 v161, v173, v172
	v_add_f32_e32 v160, v163, v160
	v_sub_f32_e32 v162, v161, v173
	v_mul_f32_e32 v160, v171, v160
	v_sub_f32_e32 v162, v172, v162
	v_add_f32_e32 v162, v162, v160
	v_add_f32_e32 v164, v161, v162
	v_mul_f32_e32 v165, v164, v164
	v_fmamk_f32 v160, v165, 0x3e9b6dac, v233
	v_fmaak_f32 v193, v165, v160, 0x3f2aaada
	v_cvt_f32_i32_e32 v160, v168
	v_sub_f32_e32 v161, v164, v161
	v_sub_f32_e32 v161, v162, v161
	v_ldexp_f32 v166, v161, 1
	v_mul_f32_e32 v161, v164, v165
	v_ldexp_f32 v163, v164, 1
	v_pk_mul_f32 v[164:165], v[160:161], v[192:193]
	s_nop 0
	v_fma_f32 v162, v160, s38, -v164
	v_fmac_f32_e32 v162, 0xb102e308, v160
	v_pk_add_f32 v[160:161], v[164:165], v[162:163]
	s_nop 0
	v_sub_f32_e32 v163, v161, v163
	v_sub_f32_e32 v163, v165, v163
	v_add_f32_e32 v167, v166, v163
	v_mov_b32_e32 v166, v164
	v_pk_add_f32 v[164:165], v[160:161], v[164:165] neg_lo:[0,1] neg_hi:[0,1]
	v_pk_add_f32 v[168:169], v[160:161], v[166:167]
	v_mov_b32_e32 v163, v160
	v_mov_b32_e32 v165, v169
	v_pk_add_f32 v[170:171], v[162:163], v[164:165] neg_lo:[0,1] neg_hi:[0,1]
	v_pk_add_f32 v[162:163], v[162:163], v[164:165]
	v_mov_b32_e32 v166, v167
	v_pk_add_f32 v[164:165], v[162:163], v[160:161] op_sel:[1,0] op_sel_hi:[0,1] neg_lo:[0,1] neg_hi:[0,1]
	v_pk_add_f32 v[172:173], v[168:169], v[164:165] op_sel_hi:[1,0] neg_lo:[0,1] neg_hi:[0,1]
	v_mov_b32_e32 v168, v169
	v_mov_b32_e32 v169, v163
	v_pk_mov_b32 v[164:165], v[160:161], v[164:165] op_sel:[1,0]
	v_mov_b32_e32 v167, v160
	v_pk_add_f32 v[164:165], v[168:169], v[164:165] neg_lo:[0,1] neg_hi:[0,1]
	v_mov_b32_e32 v172, v170
	v_pk_add_f32 v[160:161], v[166:167], v[164:165] neg_lo:[0,1] neg_hi:[0,1]
	v_mov_b32_e32 v171, v163
	v_pk_add_f32 v[164:165], v[172:173], v[160:161]
	s_nop 0
	v_pk_add_f32 v[166:167], v[164:165], v[164:165] op_sel:[0,1] op_sel_hi:[1,0]
	s_nop 0
	v_pk_add_f32 v[162:163], v[162:163], v[166:167] op_sel:[1,0] op_sel_hi:[0,1]
	v_mov_b32_e32 v165, v162
	v_pk_add_f32 v[168:169], v[164:165], v[170:171] neg_lo:[0,1] neg_hi:[0,1]
	v_mov_b32_e32 v161, v166
	v_sub_f32_e32 v163, v164, v168
	v_pk_add_f32 v[160:161], v[160:161], v[168:169] neg_lo:[0,1] neg_hi:[0,1]
	v_sub_f32_e32 v163, v170, v163
	v_add_f32_e32 v160, v160, v163
	v_add_f32_e32 v160, v160, v161
	v_add_f32_e32 v160, v162, v160
	v_cndmask_b32_e64 v160, v234, v160, s[16:17]
	v_cmp_ngt_f32_e64 s[16:17], -1.0, v174
	s_nop 1
	v_cndmask_b32_e64 v160, v235, v160, s[16:17]
	v_cmp_neq_f32_e64 s[16:17], -1.0, v174
	s_nop 1
	v_cndmask_b32_e64 v160, v236, v160, s[16:17]
	v_cmp_lt_f32_e64 s[16:17], |v174|, s40
	s_nop 1
	v_cndmask_b32_e64 v160, v160, v174, s[16:17]
	v_xor_b32_e32 v162, 0x80000000, v160

; DI uint2 pk4(f32x4 v) { return make_uint2(pk2(v[0], v[1]), pk2(v[2], v[3])); }
; DI void row_stats(const float (&v)[16], float& mean, float& rstd) {
;     float s = 0.f;
; #pragma unroll
;     for (int i = 0; i < 16; ++i) s += v[i];
;     mean = wsum(s) * (1.f / 1024.f);
;     float q = 0.f;
; #pragma unroll
;     for (int i = 0; i < 16; ++i) { float d = v[i] - mean; q += d * d; }
;     rstd = rsqrtf(wsum(q) * (1.f / 1024.f) + 1e-5f);
; }
; DI void phase1(const Params& p, unsigned char* smem) {
;     ...
;         for (int rr = 0; rr < 4; ++rr) {
;             const int row = row0 + rr;
;             float mean, rstd; row_stats(vv[rr], mean, rstd);
;             const float* mb = mod + (row >> 13) * 6144;
;             float ga[8];
; #pragma unroll
;             for (int j = 0; j < 8; ++j) ga[j] = 0.f;
; #pragma unroll
;             for (int i = 0; i < 4; ++i) {
;                 int c = i * 256 + lane * 4;
;                 float4 sh = *(const float4*)(mb + c), sc = *(const float4*)(mb + 1024 + c);
;                 f32x4 o;
;                 o[0] = (vv[rr][4 * i] - mean) * rstd * (1.f + sc.x) + sh.x;
;                 o[1] = (vv[rr][4 * i + 1] - mean) * rstd * (1.f + sc.y) + sh.y;
;                 o[2] = (vv[rr][4 * i + 2] - mean) * rstd * (1.f + sc.z) + sh.z;
;                 o[3] = (vv[rr][4 * i + 3] - mean) * rstd * (1.f + sc.w) + sh.w;
;                 *(uint2*)(h1 + (size_t)row * 1024 + c) = pk4(o);
.LBB0_205:
	s_or_b64 exec, exec, s[28:29]
	ds_read_b128 v[160:163], v237 offset:5120
	ds_read_b128 v[164:167], v237 offset:1024
	s_waitcnt vmcnt(12)
	v_add_f32_e32 v170, 0, v156
	v_add_f32_e32 v170, v170, v157
	v_add_f32_e32 v170, v170, v158
	v_add_f32_e32 v170, v170, v159
	v_add_f32_e32 v170, v170, v152
	v_add_f32_e32 v170, v170, v153
	v_add_f32_e32 v170, v170, v154
	v_add_f32_e32 v170, v170, v155
	v_add_f32_e32 v170, v170, v148
	v_add_f32_e32 v170, v170, v149
	v_add_f32_e32 v170, v170, v150
	v_add_f32_e32 v170, v170, v151
	v_add_f32_e32 v170, v170, v144
	v_add_f32_e32 v170, v170, v145
	v_add_f32_e32 v170, v170, v146
	v_add_f32_e32 v170, v170, v147
	v_lshlrev_b64 v[168:169], 11, v[202:203]
	s_nop 0
	v_add_f32_dpp v170, v170, v170 quad_perm:[1,0,3,2] row_mask:0xf bank_mask:0xf bound_ctrl:1
	s_nop 1
	v_add_f32_dpp v170, v170, v170 quad_perm:[2,3,0,1] row_mask:0xf bank_mask:0xf bound_ctrl:1
	s_nop 1
	v_add_f32_dpp v170, v170, v170 row_half_mirror row_mask:0xf bank_mask:0xf bound_ctrl:1
	s_nop 1
	v_add_f32_dpp v170, v170, v170 row_mirror row_mask:0xf bank_mask:0xf bound_ctrl:1
	s_nop 0
	v_readlane_b32 s17, v170, 16
	v_readlane_b32 s16, v170, 0
	v_readlane_b32 s18, v170, 32
	v_readlane_b32 s19, v170, 48
	v_mov_b32_e32 v170, s17
	v_add_f32_e32 v170, s16, v170
	v_add_f32_e32 v170, s18, v170
	v_add_f32_e32 v170, s19, v170
	v_mul_f32_e32 v170, 0x3a800000, v170
	v_pk_add_f32 v[156:157], v[156:157], v[170:171] op_sel_hi:[1,0] neg_lo:[0,1] neg_hi:[0,1]
	v_pk_add_f32 v[158:159], v[158:159], v[170:171] op_sel_hi:[1,0] neg_lo:[0,1] neg_hi:[0,1]
	v_pk_add_f32 v[214:215], v[148:149], v[170:171] op_sel_hi:[1,0] neg_lo:[0,1] neg_hi:[0,1]
	v_pk_add_f32 v[148:149], v[146:147], v[170:171] op_sel_hi:[1,0] neg_lo:[0,1] neg_hi:[0,1]
	v_pk_mul_f32 v[146:147], v[156:157], v[156:157]
	v_pk_add_f32 v[212:213], v[150:151], v[170:171] op_sel_hi:[1,0] neg_lo:[0,1] neg_hi:[0,1]
	v_pk_add_f32 v[150:151], v[144:145], v[170:171] op_sel_hi:[1,0] neg_lo:[0,1] neg_hi:[0,1]
	v_pk_mul_f32 v[144:145], v[158:159], v[158:159]
	v_add_f32_e32 v146, v146, v147
	v_pk_add_f32 v[174:175], v[152:153], v[170:171] op_sel_hi:[1,0] neg_lo:[0,1] neg_hi:[0,1]
	v_add_f32_e32 v144, v144, v146
	v_pk_add_f32 v[172:173], v[154:155], v[170:171] op_sel_hi:[1,0] neg_lo:[0,1] neg_hi:[0,1]
	v_pk_mul_f32 v[154:155], v[174:175], v[174:175]
	v_add_f32_e32 v144, v145, v144
	v_add_f32_e32 v144, v154, v144
	v_pk_mul_f32 v[152:153], v[172:173], v[172:173]
	v_add_f32_e32 v144, v155, v144
	v_add_f32_e32 v144, v152, v144
	v_pk_mul_f32 v[216:217], v[214:215], v[214:215]
	v_add_f32_e32 v144, v153, v144
	v_add_f32_e32 v144, v216, v144
	v_pk_mul_f32 v[170:171], v[212:213], v[212:213]
	v_add_f32_e32 v144, v217, v144
	v_add_f32_e32 v144, v170, v144
	v_pk_mul_f32 v[220:221], v[150:151], v[150:151]
	v_add_f32_e32 v144, v171, v144
	v_add_f32_e32 v144, v220, v144
	v_pk_mul_f32 v[218:219], v[148:149], v[148:149]
	v_add_f32_e32 v144, v221, v144
	v_add_f32_e32 v144, v218, v144
	v_add_f32_e32 v144, v219, v144
	s_waitcnt lgkmcnt(1)
	v_pk_add_f32 v[154:155], v[162:163], 1.0 op_sel_hi:[1,0]
	v_add_f32_dpp v144, v144, v144 quad_perm:[1,0,3,2] row_mask:0xf bank_mask:0xf bound_ctrl:1
	v_pk_add_f32 v[146:147], v[160:161], 1.0 op_sel_hi:[1,0]
	s_nop 0
	v_add_f32_dpp v144, v144, v144 quad_perm:[2,3,0,1] row_mask:0xf bank_mask:0xf bound_ctrl:1
	s_nop 1
	v_add_f32_dpp v144, v144, v144 row_half_mirror row_mask:0xf bank_mask:0xf bound_ctrl:1
	s_nop 1
	v_add_f32_dpp v144, v144, v144 row_mirror row_mask:0xf bank_mask:0xf bound_ctrl:1
	s_nop 0
	v_readlane_b32 s17, v144, 16
	v_readlane_b32 s16, v144, 0
	v_readlane_b32 s18, v144, 32
	v_readlane_b32 s19, v144, 48
	v_mov_b32_e32 v144, s17
	v_add_f32_e32 v144, s16, v144
	v_add_f32_e32 v144, s18, v144
	v_add_f32_e32 v144, s19, v144
	v_fmamk_f32 v144, v144, 0x3a800000, v232
	v_mul_f32_e32 v145, 0x4b800000, v144
	v_cmp_gt_f32_e64 s[16:17], s36, v144
	s_nop 1
	v_cndmask_b32_e64 v144, v144, v145, s[16:17]
	v_rsq_f32_e32 v152, v144
	v_lshl_add_u64 v[144:145], v[184:185], 0, v[168:169]
	v_mul_f32_e32 v153, 0x45800000, v152
	v_cndmask_b32_e64 v162, v152, v153, s[16:17]
	v_pk_mul_f32 v[152:153], v[156:157], v[162:163] op_sel_hi:[1,0]
	v_pk_mul_f32 v[168:169], v[214:215], v[162:163] op_sel_hi:[1,0]
	s_waitcnt lgkmcnt(0)
	v_pk_fma_f32 v[152:153], v[146:147], v[152:153], v[164:165]
	v_pk_mul_f32 v[146:147], v[158:159], v[162:163] op_sel_hi:[1,0]
	v_pk_mul_f32 v[164:165], v[174:175], v[162:163] op_sel_hi:[1,0]
	v_pk_fma_f32 v[146:147], v[154:155], v[146:147], v[166:167]
	v_cvt_pk_bf16_f32 v154, v152, v153
	v_cvt_pk_bf16_f32 v155, v146, v147
	global_store_dwordx2 v[144:145], v[154:155], off
	ds_read_b128 v[154:157], v237 offset:6144
	s_nop 0
	ds_read_b128 v[158:161], v237 offset:2048
	v_pk_mul_f32 v[166:167], v[172:173], v[162:163] op_sel_hi:[1,0]
	v_pk_mul_f32 v[170:171], v[212:213], v[162:163] op_sel_hi:[1,0]
	v_pk_mul_f32 v[172:173], v[150:151], v[162:163] op_sel_hi:[1,0]
	v_pk_mul_f32 v[162:163], v[148:149], v[162:163] op_sel_hi:[1,0]
	v_fma_f32 v174, v0, v152, 0
	v_fma_f32 v175, v1, v152, 0
	v_fma_f32 v177, v2, v152, 0
	v_fma_f32 v187, v3, v152, 0
	v_fma_f32 v189, v4, v152, 0
	v_fma_f32 v191, v5, v152, 0
	v_fma_f32 v193, v6, v152, 0
	v_fma_f32 v203, v7, v152, 0
	v_fmac_f32_e32 v174, v8, v153
	v_fmac_f32_e32 v175, v9, v153
	v_fmac_f32_e32 v177, v10, v153
	v_fmac_f32_e32 v187, v11, v153
	v_fmac_f32_e32 v189, v12, v153
	v_fmac_f32_e32 v191, v13, v153
	v_fmac_f32_e32 v193, v14, v153
	v_fmac_f32_e32 v203, v15, v153
	v_fmac_f32_e32 v174, v16, v146
	v_fmac_f32_e32 v175, v17, v146
	v_fmac_f32_e32 v177, v18, v146
	v_fmac_f32_e32 v187, v19, v146
	v_fmac_f32_e32 v189, v20, v146
	v_fmac_f32_e32 v191, v21, v146
	v_fmac_f32_e32 v193, v22, v146
	v_fmac_f32_e32 v203, v23, v146
	v_fmac_f32_e32 v174, v24, v147
	v_fmac_f32_e32 v175, v25, v147
	v_fmac_f32_e32 v177, v26, v147
	v_fmac_f32_e32 v187, v27, v147
	v_fmac_f32_e32 v189, v28, v147
	v_fmac_f32_e32 v191, v29, v147
	v_fmac_f32_e32 v193, v30, v147
	v_fmac_f32_e32 v203, v31, v147
	s_waitcnt lgkmcnt(1)
; DI uint2 pk4(f32x4 v) { return make_uint2(pk2(v[0], v[1]), pk2(v[2], v[3])); }
; DI void phase1(const Params& p, unsigned char* smem) {
;     ...
;             for (int i = 0; i < 4; ++i) {
;                 int c = i * 256 + lane * 4;
;                 float4 sh = *(const float4*)(mb + c), sc = *(const float4*)(mb + 1024 + c);
;                 f32x4 o;
;                 o[0] = (vv[rr][4 * i] - mean) * rstd * (1.f + sc.x) + sh.x;
;                 o[1] = (vv[rr][4 * i + 1] - mean) * rstd * (1.f + sc.y) + sh.y;
;                 o[2] = (vv[rr][4 * i + 2] - mean) * rstd * (1.f + sc.z) + sh.z;
;                 o[3] = (vv[rr][4 * i + 3] - mean) * rstd * (1.f + sc.w) + sh.w;
;                 *(uint2*)(h1 + (size_t)row * 1024 + c) = pk4(o);
; #pragma unroll
;                 for (int e = 0; e < 4; ++e) {
;                     const float4 w0 = gw0[i * 4 + e], w1 = gw1[i * 4 + e];
;                     ga[0] += o[e] * w0.x; ga[1] += o[e] * w0.y; ga[2] += o[e] * w0.z; ga[3] += o[e] * w0.w;
;                     ga[4] += o[e] * w1.x; ga[5] += o[e] * w1.y; ga[6] += o[e] * w1.z; ga[7] += o[e] * w1.w;
;                 }
;             }
; #pragma unroll
;             for (int j = 0; j < 8; ++j) ga[j] = wsum(ga[j]);
	v_pk_add_f32 v[154:155], v[154:155], 1.0 op_sel_hi:[1,0]
	v_pk_add_f32 v[156:157], v[156:157], 1.0 op_sel_hi:[1,0]
	s_waitcnt lgkmcnt(0)
	v_pk_fma_f32 v[164:165], v[164:165], v[154:155], v[158:159]
	v_pk_fma_f32 v[166:167], v[166:167], v[156:157], v[160:161]
	v_cvt_pk_bf16_f32 v154, v164, v165
	v_cvt_pk_bf16_f32 v155, v166, v167
	global_store_dwordx2 v[144:145], v[154:155], off offset:512
	ds_read_b128 v[154:157], v237 offset:7168
	s_nop 0
	ds_read_b128 v[158:161], v237 offset:3072
	v_fmac_f32_e32 v174, v32, v164
	v_fmac_f32_e32 v175, v33, v164
	v_fmac_f32_e32 v177, v34, v164
	v_fmac_f32_e32 v187, v35, v164
	v_fmac_f32_e32 v189, v36, v164
	v_fmac_f32_e32 v191, v37, v164
	v_fmac_f32_e32 v193, v38, v164
	v_fmac_f32_e32 v203, v39, v164
	v_fmac_f32_e32 v174, v40, v165
	v_fmac_f32_e32 v175, v41, v165
	v_fmac_f32_e32 v177, v42, v165
	v_fmac_f32_e32 v187, v43, v165
	v_fmac_f32_e32 v189, v44, v165
	v_fmac_f32_e32 v191, v45, v165
	v_fmac_f32_e32 v193, v46, v165
	v_fmac_f32_e32 v203, v47, v165
	v_fmac_f32_e32 v174, v48, v166
	v_fmac_f32_e32 v175, v49, v166
	v_fmac_f32_e32 v177, v50, v166
	v_fmac_f32_e32 v187, v51, v166
	v_fmac_f32_e32 v189, v52, v166
	v_fmac_f32_e32 v191, v53, v166
	v_fmac_f32_e32 v193, v54, v166
	v_fmac_f32_e32 v203, v55, v166
	v_fmac_f32_e32 v174, v56, v167
	v_fmac_f32_e32 v175, v57, v167
	v_fmac_f32_e32 v177, v58, v167
	v_fmac_f32_e32 v187, v59, v167
	v_fmac_f32_e32 v189, v60, v167
	v_fmac_f32_e32 v191, v61, v167
	v_fmac_f32_e32 v193, v62, v167
	v_fmac_f32_e32 v203, v63, v167
	s_waitcnt lgkmcnt(1)
	v_pk_add_f32 v[148:149], v[154:155], 1.0 op_sel_hi:[1,0]
	v_pk_add_f32 v[150:151], v[156:157], 1.0 op_sel_hi:[1,0]
	s_waitcnt lgkmcnt(0)
	v_pk_fma_f32 v[156:157], v[168:169], v[148:149], v[158:159]
	v_pk_fma_f32 v[158:159], v[170:171], v[150:151], v[160:161]
	v_cvt_pk_bf16_f32 v148, v156, v157
	v_cvt_pk_bf16_f32 v149, v158, v159
	global_store_dwordx2 v[144:145], v[148:149], off offset:1024
	ds_read_b128 v[148:151], v237 offset:4096
	s_nop 0
	ds_read_b128 v[152:155], v237 offset:8192
	v_fmac_f32_e32 v174, v64, v156
	v_fmac_f32_e32 v175, v65, v156
	v_fmac_f32_e32 v177, v66, v156
	v_fmac_f32_e32 v187, v67, v156
	v_fmac_f32_e32 v189, v68, v156
	v_fmac_f32_e32 v191, v69, v156
	v_fmac_f32_e32 v193, v70, v156
	v_fmac_f32_e32 v203, v71, v156
	v_fmac_f32_e32 v174, v72, v157
	v_fmac_f32_e32 v175, v73, v157
	v_fmac_f32_e32 v177, v74, v157
	v_fmac_f32_e32 v187, v75, v157
	v_fmac_f32_e32 v189, v76, v157
	v_fmac_f32_e32 v191, v77, v157
	v_fmac_f32_e32 v193, v78, v157
	v_fmac_f32_e32 v203, v79, v157
	v_fmac_f32_e32 v174, v80, v158
	v_fmac_f32_e32 v175, v81, v158
	v_fmac_f32_e32 v177, v82, v158
	v_fmac_f32_e32 v187, v83, v158
	v_fmac_f32_e32 v189, v84, v158
	v_fmac_f32_e32 v191, v85, v158
	v_fmac_f32_e32 v193, v86, v158
	v_fmac_f32_e32 v203, v87, v158
	v_fmac_f32_e32 v174, v88, v159
	v_fmac_f32_e32 v175, v89, v159
	v_fmac_f32_e32 v177, v90, v159
	v_fmac_f32_e32 v187, v91, v159
	v_fmac_f32_e32 v189, v92, v159
	v_fmac_f32_e32 v191, v93, v159
	v_fmac_f32_e32 v193, v94, v159
	v_fmac_f32_e32 v203, v95, v159
	s_waitcnt lgkmcnt(0)
	v_pk_add_f32 v[146:147], v[152:153], 1.0 op_sel_hi:[1,0]
	s_nop 0
	v_pk_fma_f32 v[146:147], v[172:173], v[146:147], v[148:149]
	v_pk_add_f32 v[152:153], v[154:155], 1.0 op_sel_hi:[1,0]
	v_fmac_f32_e32 v174, v96, v146
	v_fmac_f32_e32 v175, v97, v146
	v_fmac_f32_e32 v177, v98, v146
	v_fmac_f32_e32 v187, v99, v146
	v_fmac_f32_e32 v189, v100, v146
	v_fmac_f32_e32 v191, v101, v146
	v_fmac_f32_e32 v193, v102, v146
	v_fmac_f32_e32 v203, v103, v146
	v_pk_fma_f32 v[148:149], v[162:163], v[152:153], v[150:151]
	v_fmac_f32_e32 v174, v104, v147
	v_fmac_f32_e32 v175, v105, v147
	v_fmac_f32_e32 v177, v106, v147
	v_fmac_f32_e32 v187, v107, v147
	v_fmac_f32_e32 v189, v108, v147
	v_fmac_f32_e32 v191, v109, v147
	v_fmac_f32_e32 v193, v110, v147
	v_fmac_f32_e32 v203, v111, v147
	v_fmac_f32_e32 v174, v112, v148
	v_fmac_f32_e32 v175, v113, v148
	v_fmac_f32_e32 v177, v114, v148
	v_fmac_f32_e32 v187, v115, v148
	v_fmac_f32_e32 v189, v116, v148
	v_fmac_f32_e32 v191, v117, v148
	v_fmac_f32_e32 v193, v118, v148
	v_fmac_f32_e32 v203, v119, v148
	v_cvt_pk_bf16_f32 v150, v146, v147
	v_cvt_pk_bf16_f32 v151, v148, v149
	v_fmac_f32_e32 v174, v120, v149
	v_fmac_f32_e32 v175, v121, v149
	v_fmac_f32_e32 v177, v122, v149
	v_fmac_f32_e32 v187, v123, v149
	v_fmac_f32_e32 v189, v124, v149
	v_fmac_f32_e32 v191, v125, v149
	v_fmac_f32_e32 v193, v126, v149
	v_fmac_f32_e32 v203, v127, v149
	global_store_dwordx2 v[144:145], v[150:151], off offset:1536
	v_add_f32_dpp v144, v174, v174 quad_perm:[1,0,3,2] row_mask:0xf bank_mask:0xf bound_ctrl:1
	v_add_f32_dpp v145, v175, v175 quad_perm:[1,0,3,2] row_mask:0xf bank_mask:0xf bound_ctrl:1
	v_add_f32_dpp v146, v177, v177 quad_perm:[1,0,3,2] row_mask:0xf bank_mask:0xf bound_ctrl:1
	v_add_f32_dpp v147, v187, v187 quad_perm:[1,0,3,2] row_mask:0xf bank_mask:0xf bound_ctrl:1
	v_add_f32_dpp v148, v189, v189 quad_perm:[1,0,3,2] row_mask:0xf bank_mask:0xf bound_ctrl:1
	v_add_f32_dpp v149, v191, v191 quad_perm:[1,0,3,2] row_mask:0xf bank_mask:0xf bound_ctrl:1
	v_add_f32_dpp v150, v193, v193 quad_perm:[1,0,3,2] row_mask:0xf bank_mask:0xf bound_ctrl:1
	v_add_f32_dpp v151, v203, v203 quad_perm:[1,0,3,2] row_mask:0xf bank_mask:0xf bound_ctrl:1
	v_add_f32_dpp v144, v144, v144 quad_perm:[2,3,0,1] row_mask:0xf bank_mask:0xf bound_ctrl:1
	v_add_f32_dpp v145, v145, v145 quad_perm:[2,3,0,1] row_mask:0xf bank_mask:0xf bound_ctrl:1
	v_add_f32_dpp v146, v146, v146 quad_perm:[2,3,0,1] row_mask:0xf bank_mask:0xf bound_ctrl:1
	v_add_f32_dpp v147, v147, v147 quad_perm:[2,3,0,1] row_mask:0xf bank_mask:0xf bound_ctrl:1
; DI float logsig(float x) { return (x < 0.f) ? (x - log1pf(__expf(x))) : (-log1pf(__expf(-x))); }
; DI float wsum(float v) {
;     v += dpp_f(v, 0); v += dpp_f(v, 1); v += dpp_f(v, 2); v += dpp_f(v, 3);
;     const int x = __builtin_bit_cast(int, v);
;     return __builtin_bit_cast(float, __builtin_amdgcn_readlane(x, 0)) + __builtin_bit_cast(float, __builtin_amdgcn_readlane(x, 16))
;          + __builtin_bit_cast(float, __builtin_amdgcn_readlane(x, 32)) + __builtin_bit_cast(float, __builtin_amdgcn_readlane(x, 48));
; DI void phase1(const Params& p, unsigned char* smem) {
;     ...
; #pragma unroll
;             for (int j = 0; j < 8; ++j) ga[j] = wsum(ga[j]);
;             if (lane < 8) {
;                 float val = ga[0];
; #pragma unroll
;                 for (int j = 1; j < 8; ++j) val = (lane == j) ? ga[j] : val;
;                 val += p.in[5][2048 + lane];
;                 const int b = row >> 13, sidx = row & 8191;
;                 if (lane < 4) ig[(size_t)(b * 4 + lane) * 8192 + sidx] = val;
;                 else lf[(size_t)(b * 4 + lane - 4) * 8192 + sidx] = logsig(val);
	v_add_f32_dpp v148, v148, v148 quad_perm:[2,3,0,1] row_mask:0xf bank_mask:0xf bound_ctrl:1
	v_add_f32_dpp v149, v149, v149 quad_perm:[2,3,0,1] row_mask:0xf bank_mask:0xf bound_ctrl:1
	v_add_f32_dpp v150, v150, v150 quad_perm:[2,3,0,1] row_mask:0xf bank_mask:0xf bound_ctrl:1
	v_add_f32_dpp v151, v151, v151 quad_perm:[2,3,0,1] row_mask:0xf bank_mask:0xf bound_ctrl:1
	v_add_f32_dpp v144, v144, v144 row_half_mirror row_mask:0xf bank_mask:0xf bound_ctrl:1
	v_add_f32_dpp v145, v145, v145 row_half_mirror row_mask:0xf bank_mask:0xf bound_ctrl:1
	v_add_f32_dpp v146, v146, v146 row_half_mirror row_mask:0xf bank_mask:0xf bound_ctrl:1
	v_add_f32_dpp v147, v147, v147 row_half_mirror row_mask:0xf bank_mask:0xf bound_ctrl:1
	v_add_f32_dpp v148, v148, v148 row_half_mirror row_mask:0xf bank_mask:0xf bound_ctrl:1
	v_add_f32_dpp v149, v149, v149 row_half_mirror row_mask:0xf bank_mask:0xf bound_ctrl:1
	v_add_f32_dpp v150, v150, v150 row_half_mirror row_mask:0xf bank_mask:0xf bound_ctrl:1
	v_add_f32_dpp v151, v151, v151 row_half_mirror row_mask:0xf bank_mask:0xf bound_ctrl:1
	v_add_f32_dpp v144, v144, v144 row_mirror row_mask:0xf bank_mask:0xf bound_ctrl:1
	v_add_f32_dpp v145, v145, v145 row_mirror row_mask:0xf bank_mask:0xf bound_ctrl:1
	v_add_f32_dpp v146, v146, v146 row_mirror row_mask:0xf bank_mask:0xf bound_ctrl:1
	v_add_f32_dpp v147, v147, v147 row_mirror row_mask:0xf bank_mask:0xf bound_ctrl:1
	v_add_f32_dpp v148, v148, v148 row_mirror row_mask:0xf bank_mask:0xf bound_ctrl:1
	v_add_f32_dpp v149, v149, v149 row_mirror row_mask:0xf bank_mask:0xf bound_ctrl:1
	v_add_f32_dpp v150, v150, v150 row_mirror row_mask:0xf bank_mask:0xf bound_ctrl:1
	v_add_f32_dpp v151, v151, v151 row_mirror row_mask:0xf bank_mask:0xf bound_ctrl:1
	v_readlane_b32 s16, v144, 0
	v_readlane_b32 s31, v144, 16
	v_readlane_b32 s17, v144, 32
	v_readlane_b32 s30, v144, 48
	v_readlane_b32 s34, v145, 0
	v_readlane_b32 s42, v145, 16
	v_readlane_b32 s35, v145, 32
	v_readlane_b32 s41, v145, 48
	v_readlane_b32 s43, v146, 0
	v_readlane_b32 s46, v146, 16
	v_readlane_b32 s44, v146, 32
	v_readlane_b32 s45, v146, 48
	v_readlane_b32 s47, v147, 0
	v_readlane_b32 s50, v147, 16
	v_readlane_b32 s48, v147, 32
	v_readlane_b32 s49, v147, 48
	v_readlane_b32 s51, v148, 0
	v_readlane_b32 s55, v148, 16
	v_readlane_b32 s52, v148, 32
	v_readlane_b32 s53, v148, 48
	v_readlane_b32 s56, v149, 0
	v_readlane_b32 s73, v149, 16
	v_readlane_b32 s57, v149, 32
	v_readlane_b32 s72, v149, 48
	v_readlane_b32 s74, v150, 0
	v_readlane_b32 s83, v150, 16
	v_readlane_b32 s75, v150, 32
	v_readlane_b32 s82, v150, 48
	v_readlane_b32 s84, v151, 0
	v_readlane_b32 s87, v151, 16
	v_readlane_b32 s85, v151, 32
	v_readlane_b32 s86, v151, 48
	s_and_saveexec_b64 s[28:29], vcc
	s_cbranch_execz .LBB0_213
	v_mov_b32_e32 v150, s42
	v_mov_b32_e32 v151, s31
	v_mov_b32_e32 v149, s46
	v_add_f32_e32 v150, s34, v150
	v_add_f32_e32 v151, s16, v151
	v_mov_b32_e32 v148, s50
	v_add_f32_e32 v149, s43, v149
	v_add_f32_e32 v150, s35, v150
	v_add_f32_e32 v151, s17, v151
	v_mov_b32_e32 v147, s55
	v_add_f32_e32 v148, s47, v148
	v_add_f32_e32 v149, s44, v149
	v_add_f32_e32 v150, s41, v150
	v_add_f32_e32 v151, s30, v151
	v_mov_b32_e32 v146, s73
	v_add_f32_e32 v147, s51, v147
	v_add_f32_e32 v148, s48, v148
	v_add_f32_e32 v149, s45, v149
	v_cndmask_b32_e64 v150, v151, v150, s[0:1]
	v_mov_b32_e32 v145, s83
	v_add_f32_e32 v146, s56, v146
	v_add_f32_e32 v147, s52, v147
	v_add_f32_e32 v148, s49, v148
	v_cndmask_b32_e64 v149, v150, v149, s[14:15]
	v_mov_b32_e32 v144, s87
	v_add_f32_e32 v145, s74, v145
	v_add_f32_e32 v146, s57, v146
	v_add_f32_e32 v147, s53, v147
	v_cndmask_b32_e64 v148, v149, v148, s[4:5]
	v_add_f32_e32 v144, s84, v144
	v_add_f32_e32 v145, s75, v145
	v_add_f32_e32 v146, s72, v146
	v_cndmask_b32_e64 v147, v148, v147, s[6:7]
	v_add_f32_e32 v144, s85, v144
	v_add_f32_e32 v145, s82, v145
	v_cndmask_b32_e64 v146, v147, v146, s[8:9]
	v_add_f32_e32 v144, s86, v144
	v_cndmask_b32_e64 v145, v146, v145, s[10:11]
	v_cndmask_b32_e64 v144, v145, v144, s[12:13]
	v_mov_b32_e32 v145, v251
	v_add_f32_e32 v146, v144, v145
	v_mov_b64_e32 v[144:145], v[210:211]
	s_and_saveexec_b64 s[30:31], s[24:25]
	s_cbranch_execz .LBB0_212
	v_cmp_ngt_f32_e64 s[16:17], 0, v146
	s_and_saveexec_b64 s[34:35], s[16:17]
	s_xor_b64 s[34:35], exec, s[34:35]
	s_cbranch_execz .LBB0_209
; DI float logsig(float x) { return (x < 0.f) ? (x - log1pf(__expf(x))) : (-log1pf(__expf(-x))); }
; DI void phase1(const Params& p, unsigned char* smem) {
;     ...
;                 const int b = row >> 13, sidx = row & 8191;
;                 if (lane < 4) ig[(size_t)(b * 4 + lane) * 8192 + sidx] = val;
;                 else lf[(size_t)(b * 4 + lane - 4) * 8192 + sidx] = logsig(val);
	v_mul_f32_e32 v144, 0xbfb8aa3b, v146
	v_exp_f32_e32 v158, v144
	s_nop 0
	v_add_f32_e32 v146, 1.0, v158
	v_frexp_mant_f32_e32 v148, v146
	v_cvt_f64_f32_e32 v[144:145], v146
	v_frexp_exp_i32_f64_e32 v144, v[144:145]
	v_cmp_gt_f32_e64 s[16:17], s37, v148
	v_add_f32_e32 v147, -1.0, v146
	v_sub_f32_e32 v149, v147, v146
	v_subbrev_co_u32_e64 v152, s[16:17], 0, v144, s[16:17]
	v_sub_u32_e32 v144, 0, v152
	v_sub_f32_e32 v147, v158, v147
	v_add_f32_e32 v149, 1.0, v149
	v_ldexp_f32 v145, v146, v144
	v_add_f32_e32 v147, v147, v149
	v_add_f32_e32 v146, -1.0, v145
	v_add_f32_e32 v148, 1.0, v145
	v_ldexp_f32 v144, v147, v144
	v_add_f32_e32 v147, 1.0, v146
	v_add_f32_e32 v149, -1.0, v148
	v_sub_f32_e32 v147, v145, v147
	v_sub_f32_e32 v145, v145, v149
	v_add_f32_e32 v147, v144, v147
	v_add_f32_e32 v144, v144, v145
	v_add_f32_e32 v153, v148, v144
	v_rcp_f32_e32 v155, v153
	v_sub_f32_e32 v145, v153, v148
	v_sub_f32_e32 v154, v144, v145
	v_add_f32_e32 v145, v146, v147
	v_mul_f32_e32 v157, v145, v155
	v_sub_f32_e32 v144, v145, v146
	v_mul_f32_e32 v146, v153, v157
	v_fma_f32 v148, v157, v153, -v146
	v_fmac_f32_e32 v148, v157, v154
	v_sub_f32_e32 v156, v147, v144
	v_add_f32_e32 v144, v146, v148
	v_sub_f32_e32 v147, v145, v144
	v_pk_add_f32 v[150:151], v[144:145], v[146:147] neg_lo:[0,1] neg_hi:[0,1]
	v_mov_b32_e32 v149, v144
	v_pk_add_f32 v[144:145], v[150:151], v[148:149] neg_lo:[0,1] neg_hi:[0,1]
	v_cmp_neq_f32_e64 s[16:17], s39, v158
	v_add_f32_e32 v145, v156, v145
	v_add_f32_e32 v144, v144, v145
	v_add_f32_e32 v145, v147, v144
	v_mul_f32_e32 v156, v155, v145
	v_mul_f32_e32 v146, v153, v156
	v_fma_f32 v148, v156, v153, -v146
	v_fmac_f32_e32 v148, v156, v154
	v_sub_f32_e32 v147, v147, v145
	v_add_f32_e32 v153, v144, v147
	v_add_f32_e32 v144, v146, v148
	v_sub_f32_e32 v147, v145, v144
	v_pk_add_f32 v[150:151], v[144:145], v[146:147] neg_lo:[0,1] neg_hi:[0,1]
	v_mov_b32_e32 v149, v144
	v_pk_add_f32 v[144:145], v[150:151], v[148:149] neg_lo:[0,1] neg_hi:[0,1]
	s_nop 0
	v_add_f32_e32 v145, v153, v145
	v_add_f32_e32 v144, v144, v145
	v_add_f32_e32 v145, v157, v156
	v_add_f32_e32 v144, v147, v144
	v_sub_f32_e32 v146, v145, v157
	v_mul_f32_e32 v144, v155, v144
	v_sub_f32_e32 v146, v156, v146
	v_add_f32_e32 v146, v146, v144
	v_add_f32_e32 v148, v145, v146
	v_mul_f32_e32 v149, v148, v148
	v_fmamk_f32 v144, v149, 0x3e9b6dac, v233
	v_fmaak_f32 v193, v149, v144, 0x3f2aaada
	v_cvt_f32_i32_e32 v144, v152
	v_sub_f32_e32 v145, v148, v145
	v_sub_f32_e32 v145, v146, v145
	v_ldexp_f32 v150, v145, 1
	v_mul_f32_e32 v145, v148, v149
	v_ldexp_f32 v147, v148, 1
	v_pk_mul_f32 v[148:149], v[144:145], v[192:193]
	s_nop 0
	v_fma_f32 v146, v144, s38, -v148
	v_fmac_f32_e32 v146, 0xb102e308, v144
	v_pk_add_f32 v[144:145], v[148:149], v[146:147]
	s_nop 0
	v_sub_f32_e32 v147, v145, v147
	v_sub_f32_e32 v147, v149, v147
	v_add_f32_e32 v151, v150, v147
	v_mov_b32_e32 v150, v148
	v_pk_add_f32 v[148:149], v[144:145], v[148:149] neg_lo:[0,1] neg_hi:[0,1]
	v_pk_add_f32 v[152:153], v[144:145], v[150:151]
	v_mov_b32_e32 v147, v144
	v_mov_b32_e32 v149, v153
	v_pk_add_f32 v[154:155], v[146:147], v[148:149] neg_lo:[0,1] neg_hi:[0,1]
	v_pk_add_f32 v[146:147], v[146:147], v[148:149]
	v_mov_b32_e32 v150, v151
	v_pk_add_f32 v[148:149], v[146:147], v[144:145] op_sel:[1,0] op_sel_hi:[0,1] neg_lo:[0,1] neg_hi:[0,1]
	v_pk_add_f32 v[156:157], v[152:153], v[148:149] op_sel_hi:[1,0] neg_lo:[0,1] neg_hi:[0,1]
	v_mov_b32_e32 v152, v153
	v_mov_b32_e32 v153, v147
	v_pk_mov_b32 v[148:149], v[144:145], v[148:149] op_sel:[1,0]
	v_mov_b32_e32 v151, v144
	v_pk_add_f32 v[148:149], v[152:153], v[148:149] neg_lo:[0,1] neg_hi:[0,1]
	v_mov_b32_e32 v156, v154
	v_pk_add_f32 v[144:145], v[150:151], v[148:149] neg_lo:[0,1] neg_hi:[0,1]
	v_mov_b32_e32 v155, v147
	v_pk_add_f32 v[148:149], v[156:157], v[144:145]
	s_nop 0
	v_pk_add_f32 v[150:151], v[148:149], v[148:149] op_sel:[0,1] op_sel_hi:[1,0]
	s_nop 0
	v_pk_add_f32 v[146:147], v[146:147], v[150:151] op_sel:[1,0] op_sel_hi:[0,1]
	v_mov_b32_e32 v149, v146
	v_pk_add_f32 v[152:153], v[148:149], v[154:155] neg_lo:[0,1] neg_hi:[0,1]
	v_mov_b32_e32 v145, v150
	v_sub_f32_e32 v147, v148, v152
	v_pk_add_f32 v[144:145], v[144:145], v[152:153] neg_lo:[0,1] neg_hi:[0,1]
	v_sub_f32_e32 v147, v154, v147
	v_add_f32_e32 v144, v144, v147
	v_add_f32_e32 v144, v144, v145
	v_add_f32_e32 v144, v146, v144
	v_cndmask_b32_e64 v144, v234, v144, s[16:17]
	v_cmp_ngt_f32_e64 s[16:17], -1.0, v158
	s_nop 1
	v_cndmask_b32_e64 v144, v235, v144, s[16:17]
	v_cmp_neq_f32_e64 s[16:17], -1.0, v158
	s_nop 1
	v_cndmask_b32_e64 v144, v236, v144, s[16:17]
	v_cmp_lt_f32_e64 s[16:17], |v158|, s40
	s_nop 1
	v_cndmask_b32_e64 v144, v144, v158, s[16:17]
	v_xor_b32_e32 v146, 0x80000000, v144

; DI uint2 pk4(f32x4 v) { return make_uint2(pk2(v[0], v[1]), pk2(v[2], v[3])); }
; DI void row_stats(const float (&v)[16], float& mean, float& rstd) {
;     float s = 0.f;
; #pragma unroll
;     for (int i = 0; i < 16; ++i) s += v[i];
;     mean = wsum(s) * (1.f / 1024.f);
;     float q = 0.f;
; #pragma unroll
;     for (int i = 0; i < 16; ++i) { float d = v[i] - mean; q += d * d; }
;     rstd = rsqrtf(wsum(q) * (1.f / 1024.f) + 1e-5f);
; }
; DI void phase1(const Params& p, unsigned char* smem) {
;     ...
;         for (int rr = 0; rr < 4; ++rr) {
;             const int row = row0 + rr;
;             float mean, rstd; row_stats(vv[rr], mean, rstd);
;             const float* mb = mod + (row >> 13) * 6144;
;             float ga[8];
; #pragma unroll
;             for (int j = 0; j < 8; ++j) ga[j] = 0.f;
; #pragma unroll
;             for (int i = 0; i < 4; ++i) {
;                 int c = i * 256 + lane * 4;
;                 float4 sh = *(const float4*)(mb + c), sc = *(const float4*)(mb + 1024 + c);
;                 f32x4 o;
;                 o[0] = (vv[rr][4 * i] - mean) * rstd * (1.f + sc.x) + sh.x;
;                 o[1] = (vv[rr][4 * i + 1] - mean) * rstd * (1.f + sc.y) + sh.y;
;                 o[2] = (vv[rr][4 * i + 2] - mean) * rstd * (1.f + sc.z) + sh.z;
;                 o[3] = (vv[rr][4 * i + 3] - mean) * rstd * (1.f + sc.w) + sh.w;
;                 *(uint2*)(h1 + (size_t)row * 1024 + c) = pk4(o);
; #pragma unroll
;                 for (int e = 0; e < 4; ++e) {
;                     const float4 w0 = gw0[i * 4 + e], w1 = gw1[i * 4 + e];
;                     ga[0] += o[e] * w0.x; ga[1] += o[e] * w0.y; ga[2] += o[e] * w0.z; ga[3] += o[e] * w0.w;
;                     ga[4] += o[e] * w1.x; ga[5] += o[e] * w1.y; ga[6] += o[e] * w1.z; ga[7] += o[e] * w1.w;
.LBB0_213:
	s_or_b64 exec, exec, s[28:29]
	ds_read_b128 v[144:147], v237 offset:5120
	ds_read_b128 v[148:151], v237 offset:1024
	s_waitcnt vmcnt(12)
	v_add_f32_e32 v154, 0, v140
	v_add_f32_e32 v154, v154, v141
	v_add_f32_e32 v154, v154, v142
	v_add_f32_e32 v154, v154, v143
	v_add_f32_e32 v154, v154, v136
	v_add_f32_e32 v154, v154, v137
	v_add_f32_e32 v154, v154, v138
	v_add_f32_e32 v154, v154, v139
	v_add_f32_e32 v154, v154, v132
	v_add_f32_e32 v154, v154, v133
	v_add_f32_e32 v154, v154, v134
	v_add_f32_e32 v154, v154, v135
	v_add_f32_e32 v154, v154, v128
	v_add_f32_e32 v154, v154, v129
	v_add_f32_e32 v154, v154, v130
	v_add_f32_e32 v154, v154, v131
	v_lshlrev_b64 v[152:153], 11, v[194:195]
	s_nop 0
	v_add_f32_dpp v154, v154, v154 quad_perm:[1,0,3,2] row_mask:0xf bank_mask:0xf bound_ctrl:1
	s_nop 1
	v_add_f32_dpp v154, v154, v154 quad_perm:[2,3,0,1] row_mask:0xf bank_mask:0xf bound_ctrl:1
	s_nop 1
	v_add_f32_dpp v154, v154, v154 row_half_mirror row_mask:0xf bank_mask:0xf bound_ctrl:1
	s_nop 1
	v_add_f32_dpp v154, v154, v154 row_mirror row_mask:0xf bank_mask:0xf bound_ctrl:1
	s_nop 0
	v_readlane_b32 s17, v154, 16
	v_readlane_b32 s16, v154, 0
	v_readlane_b32 s18, v154, 32
	v_readlane_b32 s19, v154, 48
	v_mov_b32_e32 v154, s17
	v_add_f32_e32 v154, s16, v154
	v_add_f32_e32 v154, s18, v154
	v_add_f32_e32 v154, s19, v154
	v_mul_f32_e32 v154, 0x3a800000, v154
	v_pk_add_f32 v[140:141], v[140:141], v[154:155] op_sel_hi:[1,0] neg_lo:[0,1] neg_hi:[0,1]
	v_pk_add_f32 v[142:143], v[142:143], v[154:155] op_sel_hi:[1,0] neg_lo:[0,1] neg_hi:[0,1]
	v_pk_add_f32 v[162:163], v[132:133], v[154:155] op_sel_hi:[1,0] neg_lo:[0,1] neg_hi:[0,1]
	v_pk_add_f32 v[132:133], v[130:131], v[154:155] op_sel_hi:[1,0] neg_lo:[0,1] neg_hi:[0,1]
	v_pk_mul_f32 v[130:131], v[140:141], v[140:141]
	v_pk_add_f32 v[160:161], v[134:135], v[154:155] op_sel_hi:[1,0] neg_lo:[0,1] neg_hi:[0,1]
	v_pk_add_f32 v[134:135], v[128:129], v[154:155] op_sel_hi:[1,0] neg_lo:[0,1] neg_hi:[0,1]
	v_pk_mul_f32 v[128:129], v[142:143], v[142:143]
	v_add_f32_e32 v130, v130, v131
	v_pk_add_f32 v[158:159], v[136:137], v[154:155] op_sel_hi:[1,0] neg_lo:[0,1] neg_hi:[0,1]
	v_add_f32_e32 v128, v128, v130
	v_pk_add_f32 v[156:157], v[138:139], v[154:155] op_sel_hi:[1,0] neg_lo:[0,1] neg_hi:[0,1]
	v_pk_mul_f32 v[138:139], v[158:159], v[158:159]
	v_add_f32_e32 v128, v129, v128
	v_add_f32_e32 v128, v138, v128
	v_pk_mul_f32 v[136:137], v[156:157], v[156:157]
	v_add_f32_e32 v128, v139, v128
	v_add_f32_e32 v128, v136, v128
	v_pk_mul_f32 v[164:165], v[162:163], v[162:163]
	v_add_f32_e32 v128, v137, v128
	v_add_f32_e32 v128, v164, v128
	v_pk_mul_f32 v[154:155], v[160:161], v[160:161]
	v_add_f32_e32 v128, v165, v128
	v_add_f32_e32 v128, v154, v128
	v_pk_mul_f32 v[168:169], v[134:135], v[134:135]
	v_add_f32_e32 v128, v155, v128
	v_add_f32_e32 v128, v168, v128
	v_pk_mul_f32 v[166:167], v[132:133], v[132:133]
	v_add_f32_e32 v128, v169, v128
	v_add_f32_e32 v128, v166, v128
	v_add_f32_e32 v128, v167, v128
	s_waitcnt lgkmcnt(1)
	v_pk_add_f32 v[138:139], v[146:147], 1.0 op_sel_hi:[1,0]
	v_add_f32_dpp v128, v128, v128 quad_perm:[1,0,3,2] row_mask:0xf bank_mask:0xf bound_ctrl:1
	v_pk_add_f32 v[130:131], v[144:145], 1.0 op_sel_hi:[1,0]
	s_nop 0
	v_add_f32_dpp v128, v128, v128 quad_perm:[2,3,0,1] row_mask:0xf bank_mask:0xf bound_ctrl:1
	s_nop 1
	v_add_f32_dpp v128, v128, v128 row_half_mirror row_mask:0xf bank_mask:0xf bound_ctrl:1
	s_nop 1
	v_add_f32_dpp v128, v128, v128 row_mirror row_mask:0xf bank_mask:0xf bound_ctrl:1
	s_nop 0
	v_readlane_b32 s17, v128, 16
	v_readlane_b32 s16, v128, 0
	v_readlane_b32 s18, v128, 32
	v_readlane_b32 s19, v128, 48
	v_mov_b32_e32 v128, s17
	v_add_f32_e32 v128, s16, v128
	v_add_f32_e32 v128, s18, v128
	v_add_f32_e32 v128, s19, v128
	v_fmamk_f32 v128, v128, 0x3a800000, v232
	v_mul_f32_e32 v129, 0x4b800000, v128
	v_cmp_gt_f32_e64 s[16:17], s36, v128
	s_nop 1
	v_cndmask_b32_e64 v128, v128, v129, s[16:17]
	v_rsq_f32_e32 v136, v128
	v_lshl_add_u64 v[128:129], v[184:185], 0, v[152:153]
	v_mul_f32_e32 v137, 0x45800000, v136
	v_cndmask_b32_e64 v146, v136, v137, s[16:17]
	v_pk_mul_f32 v[136:137], v[140:141], v[146:147] op_sel_hi:[1,0]
	v_pk_mul_f32 v[152:153], v[162:163], v[146:147] op_sel_hi:[1,0]
	s_waitcnt lgkmcnt(0)
	v_pk_fma_f32 v[136:137], v[130:131], v[136:137], v[148:149]
	v_pk_mul_f32 v[130:131], v[142:143], v[146:147] op_sel_hi:[1,0]
	v_pk_mul_f32 v[148:149], v[158:159], v[146:147] op_sel_hi:[1,0]
	v_pk_fma_f32 v[130:131], v[138:139], v[130:131], v[150:151]
	v_cvt_pk_bf16_f32 v138, v136, v137
	v_cvt_pk_bf16_f32 v139, v130, v131
	global_store_dwordx2 v[128:129], v[138:139], off
	ds_read_b128 v[138:141], v237 offset:6144
	s_nop 0
	ds_read_b128 v[142:145], v237 offset:2048
	v_pk_mul_f32 v[150:151], v[156:157], v[146:147] op_sel_hi:[1,0]
	v_pk_mul_f32 v[154:155], v[160:161], v[146:147] op_sel_hi:[1,0]
	v_pk_mul_f32 v[156:157], v[134:135], v[146:147] op_sel_hi:[1,0]
	v_pk_mul_f32 v[146:147], v[132:133], v[146:147] op_sel_hi:[1,0]
	v_fma_f32 v158, v0, v136, 0
	v_fma_f32 v159, v1, v136, 0
	v_fma_f32 v160, v2, v136, 0
	v_fma_f32 v161, v3, v136, 0
	v_fma_f32 v162, v4, v136, 0
	v_fma_f32 v163, v5, v136, 0
	v_fma_f32 v164, v6, v136, 0
	v_fma_f32 v165, v7, v136, 0
	v_fmac_f32_e32 v158, v8, v137
	v_fmac_f32_e32 v159, v9, v137
	v_fmac_f32_e32 v160, v10, v137
	v_fmac_f32_e32 v161, v11, v137
	v_fmac_f32_e32 v162, v12, v137
	v_fmac_f32_e32 v163, v13, v137
	v_fmac_f32_e32 v164, v14, v137
	v_fmac_f32_e32 v165, v15, v137
	v_fmac_f32_e32 v158, v16, v130
	v_fmac_f32_e32 v159, v17, v130
	v_fmac_f32_e32 v160, v18, v130
	v_fmac_f32_e32 v161, v19, v130
	v_fmac_f32_e32 v162, v20, v130
	v_fmac_f32_e32 v163, v21, v130
	v_fmac_f32_e32 v164, v22, v130
	v_fmac_f32_e32 v165, v23, v130
	v_fmac_f32_e32 v158, v24, v131
	v_fmac_f32_e32 v159, v25, v131
	v_fmac_f32_e32 v160, v26, v131
	v_fmac_f32_e32 v161, v27, v131
	v_fmac_f32_e32 v162, v28, v131
	v_fmac_f32_e32 v163, v29, v131
	v_fmac_f32_e32 v164, v30, v131
	v_fmac_f32_e32 v165, v31, v131
	s_waitcnt lgkmcnt(1)
; DI uint2 pk4(f32x4 v) { return make_uint2(pk2(v[0], v[1]), pk2(v[2], v[3])); }
; DI void phase1(const Params& p, unsigned char* smem) {
;     ...
;             for (int i = 0; i < 4; ++i) {
;                 int c = i * 256 + lane * 4;
;                 float4 sh = *(const float4*)(mb + c), sc = *(const float4*)(mb + 1024 + c);
;                 f32x4 o;
;                 o[0] = (vv[rr][4 * i] - mean) * rstd * (1.f + sc.x) + sh.x;
;                 o[1] = (vv[rr][4 * i + 1] - mean) * rstd * (1.f + sc.y) + sh.y;
;                 o[2] = (vv[rr][4 * i + 2] - mean) * rstd * (1.f + sc.z) + sh.z;
;                 o[3] = (vv[rr][4 * i + 3] - mean) * rstd * (1.f + sc.w) + sh.w;
;                 *(uint2*)(h1 + (size_t)row * 1024 + c) = pk4(o);
; #pragma unroll
;                 for (int e = 0; e < 4; ++e) {
;                     const float4 w0 = gw0[i * 4 + e], w1 = gw1[i * 4 + e];
;                     ga[0] += o[e] * w0.x; ga[1] += o[e] * w0.y; ga[2] += o[e] * w0.z; ga[3] += o[e] * w0.w;
;                     ga[4] += o[e] * w1.x; ga[5] += o[e] * w1.y; ga[6] += o[e] * w1.z; ga[7] += o[e] * w1.w;
;                 }
;             }
; #pragma unroll
;             for (int j = 0; j < 8; ++j) ga[j] = wsum(ga[j]);
	v_pk_add_f32 v[138:139], v[138:139], 1.0 op_sel_hi:[1,0]
	v_pk_add_f32 v[140:141], v[140:141], 1.0 op_sel_hi:[1,0]
	s_waitcnt lgkmcnt(0)
	v_pk_fma_f32 v[148:149], v[148:149], v[138:139], v[142:143]
	v_pk_fma_f32 v[150:151], v[150:151], v[140:141], v[144:145]
	v_cvt_pk_bf16_f32 v138, v148, v149
	v_cvt_pk_bf16_f32 v139, v150, v151
	global_store_dwordx2 v[128:129], v[138:139], off offset:512
	ds_read_b128 v[138:141], v237 offset:7168
	s_nop 0
	ds_read_b128 v[142:145], v237 offset:3072
	v_fmac_f32_e32 v158, v32, v148
	v_fmac_f32_e32 v159, v33, v148
	v_fmac_f32_e32 v160, v34, v148
	v_fmac_f32_e32 v161, v35, v148
	v_fmac_f32_e32 v162, v36, v148
	v_fmac_f32_e32 v163, v37, v148
	v_fmac_f32_e32 v164, v38, v148
	v_fmac_f32_e32 v165, v39, v148
	v_fmac_f32_e32 v158, v40, v149
	v_fmac_f32_e32 v159, v41, v149
	v_fmac_f32_e32 v160, v42, v149
	v_fmac_f32_e32 v161, v43, v149
	v_fmac_f32_e32 v162, v44, v149
	v_fmac_f32_e32 v163, v45, v149
	v_fmac_f32_e32 v164, v46, v149
	v_fmac_f32_e32 v165, v47, v149
	v_fmac_f32_e32 v158, v48, v150
	v_fmac_f32_e32 v159, v49, v150
	v_fmac_f32_e32 v160, v50, v150
	v_fmac_f32_e32 v161, v51, v150
	v_fmac_f32_e32 v162, v52, v150
	v_fmac_f32_e32 v163, v53, v150
	v_fmac_f32_e32 v164, v54, v150
	v_fmac_f32_e32 v165, v55, v150
	v_fmac_f32_e32 v158, v56, v151
	v_fmac_f32_e32 v159, v57, v151
	v_fmac_f32_e32 v160, v58, v151
	v_fmac_f32_e32 v161, v59, v151
	v_fmac_f32_e32 v162, v60, v151
	v_fmac_f32_e32 v163, v61, v151
	v_fmac_f32_e32 v164, v62, v151
	v_fmac_f32_e32 v165, v63, v151
	s_waitcnt lgkmcnt(1)
	v_pk_add_f32 v[132:133], v[138:139], 1.0 op_sel_hi:[1,0]
	v_pk_add_f32 v[134:135], v[140:141], 1.0 op_sel_hi:[1,0]
	s_waitcnt lgkmcnt(0)
	v_pk_fma_f32 v[140:141], v[152:153], v[132:133], v[142:143]
	v_pk_fma_f32 v[142:143], v[154:155], v[134:135], v[144:145]
	v_cvt_pk_bf16_f32 v132, v140, v141
	v_cvt_pk_bf16_f32 v133, v142, v143
	global_store_dwordx2 v[128:129], v[132:133], off offset:1024
	ds_read_b128 v[132:135], v237 offset:4096
	s_nop 0
	ds_read_b128 v[136:139], v237 offset:8192
	v_fmac_f32_e32 v158, v64, v140
	v_fmac_f32_e32 v159, v65, v140
	v_fmac_f32_e32 v160, v66, v140
	v_fmac_f32_e32 v161, v67, v140
	v_fmac_f32_e32 v162, v68, v140
	v_fmac_f32_e32 v163, v69, v140
	v_fmac_f32_e32 v164, v70, v140
	v_fmac_f32_e32 v165, v71, v140
	v_fmac_f32_e32 v158, v72, v141
	v_fmac_f32_e32 v159, v73, v141
	v_fmac_f32_e32 v160, v74, v141
	v_fmac_f32_e32 v161, v75, v141
	v_fmac_f32_e32 v162, v76, v141
	v_fmac_f32_e32 v163, v77, v141
	v_fmac_f32_e32 v164, v78, v141
	v_fmac_f32_e32 v165, v79, v141
	v_fmac_f32_e32 v158, v80, v142
	v_fmac_f32_e32 v159, v81, v142
	v_fmac_f32_e32 v160, v82, v142
	v_fmac_f32_e32 v161, v83, v142
	v_fmac_f32_e32 v162, v84, v142
	v_fmac_f32_e32 v163, v85, v142
	v_fmac_f32_e32 v164, v86, v142
	v_fmac_f32_e32 v165, v87, v142
	v_fmac_f32_e32 v158, v88, v143
	v_fmac_f32_e32 v159, v89, v143
	v_fmac_f32_e32 v160, v90, v143
	v_fmac_f32_e32 v161, v91, v143
	v_fmac_f32_e32 v162, v92, v143
	v_fmac_f32_e32 v163, v93, v143
	v_fmac_f32_e32 v164, v94, v143
	v_fmac_f32_e32 v165, v95, v143
	s_waitcnt lgkmcnt(0)
	v_pk_add_f32 v[130:131], v[136:137], 1.0 op_sel_hi:[1,0]
	s_nop 0
	v_pk_fma_f32 v[130:131], v[156:157], v[130:131], v[132:133]
	v_pk_add_f32 v[136:137], v[138:139], 1.0 op_sel_hi:[1,0]
	v_fmac_f32_e32 v158, v96, v130
	v_fmac_f32_e32 v159, v97, v130
	v_fmac_f32_e32 v160, v98, v130
	v_fmac_f32_e32 v161, v99, v130
	v_fmac_f32_e32 v162, v100, v130
	v_fmac_f32_e32 v163, v101, v130
	v_fmac_f32_e32 v164, v102, v130
	v_fmac_f32_e32 v165, v103, v130
	v_pk_fma_f32 v[132:133], v[146:147], v[136:137], v[134:135]
	v_fmac_f32_e32 v158, v104, v131
	v_fmac_f32_e32 v159, v105, v131
	v_fmac_f32_e32 v160, v106, v131
	v_fmac_f32_e32 v161, v107, v131
	v_fmac_f32_e32 v162, v108, v131
	v_fmac_f32_e32 v163, v109, v131
	v_fmac_f32_e32 v164, v110, v131
	v_fmac_f32_e32 v165, v111, v131
	v_fmac_f32_e32 v158, v112, v132
	v_fmac_f32_e32 v159, v113, v132
	v_fmac_f32_e32 v160, v114, v132
	v_fmac_f32_e32 v161, v115, v132
	v_fmac_f32_e32 v162, v116, v132
	v_fmac_f32_e32 v163, v117, v132
	v_fmac_f32_e32 v164, v118, v132
	v_fmac_f32_e32 v165, v119, v132
	v_cvt_pk_bf16_f32 v134, v130, v131
	v_cvt_pk_bf16_f32 v135, v132, v133
	v_fmac_f32_e32 v158, v120, v133
	v_fmac_f32_e32 v159, v121, v133
	v_fmac_f32_e32 v160, v122, v133
	v_fmac_f32_e32 v161, v123, v133
	v_fmac_f32_e32 v162, v124, v133
	v_fmac_f32_e32 v163, v125, v133
	v_fmac_f32_e32 v164, v126, v133
	v_fmac_f32_e32 v165, v127, v133
	global_store_dwordx2 v[128:129], v[134:135], off offset:1536
	v_add_f32_dpp v128, v158, v158 quad_perm:[1,0,3,2] row_mask:0xf bank_mask:0xf bound_ctrl:1
	v_add_f32_dpp v129, v159, v159 quad_perm:[1,0,3,2] row_mask:0xf bank_mask:0xf bound_ctrl:1
	v_add_f32_dpp v130, v160, v160 quad_perm:[1,0,3,2] row_mask:0xf bank_mask:0xf bound_ctrl:1
	v_add_f32_dpp v131, v161, v161 quad_perm:[1,0,3,2] row_mask:0xf bank_mask:0xf bound_ctrl:1
	v_add_f32_dpp v132, v162, v162 quad_perm:[1,0,3,2] row_mask:0xf bank_mask:0xf bound_ctrl:1
	v_add_f32_dpp v133, v163, v163 quad_perm:[1,0,3,2] row_mask:0xf bank_mask:0xf bound_ctrl:1
	v_add_f32_dpp v134, v164, v164 quad_perm:[1,0,3,2] row_mask:0xf bank_mask:0xf bound_ctrl:1
	v_add_f32_dpp v135, v165, v165 quad_perm:[1,0,3,2] row_mask:0xf bank_mask:0xf bound_ctrl:1
	v_add_f32_dpp v128, v128, v128 quad_perm:[2,3,0,1] row_mask:0xf bank_mask:0xf bound_ctrl:1
	v_add_f32_dpp v129, v129, v129 quad_perm:[2,3,0,1] row_mask:0xf bank_mask:0xf bound_ctrl:1
	v_add_f32_dpp v130, v130, v130 quad_perm:[2,3,0,1] row_mask:0xf bank_mask:0xf bound_ctrl:1
	v_add_f32_dpp v131, v131, v131 quad_perm:[2,3,0,1] row_mask:0xf bank_mask:0xf bound_ctrl:1
; DI float logsig(float x) { return (x < 0.f) ? (x - log1pf(__expf(x))) : (-log1pf(__expf(-x))); }
; DI float wsum(float v) {
;     v += dpp_f(v, 0); v += dpp_f(v, 1); v += dpp_f(v, 2); v += dpp_f(v, 3);
;     const int x = __builtin_bit_cast(int, v);
;     return __builtin_bit_cast(float, __builtin_amdgcn_readlane(x, 0)) + __builtin_bit_cast(float, __builtin_amdgcn_readlane(x, 16))
;          + __builtin_bit_cast(float, __builtin_amdgcn_readlane(x, 32)) + __builtin_bit_cast(float, __builtin_amdgcn_readlane(x, 48));
; DI void phase1(const Params& p, unsigned char* smem) {
;     ...
; #pragma unroll
;             for (int j = 0; j < 8; ++j) ga[j] = wsum(ga[j]);
;             if (lane < 8) {
;                 float val = ga[0];
; #pragma unroll
;                 for (int j = 1; j < 8; ++j) val = (lane == j) ? ga[j] : val;
;                 val += p.in[5][2048 + lane];
;                 const int b = row >> 13, sidx = row & 8191;
;                 if (lane < 4) ig[(size_t)(b * 4 + lane) * 8192 + sidx] = val;
;                 else lf[(size_t)(b * 4 + lane - 4) * 8192 + sidx] = logsig(val);
	v_add_f32_dpp v132, v132, v132 quad_perm:[2,3,0,1] row_mask:0xf bank_mask:0xf bound_ctrl:1
	v_add_f32_dpp v133, v133, v133 quad_perm:[2,3,0,1] row_mask:0xf bank_mask:0xf bound_ctrl:1
	v_add_f32_dpp v134, v134, v134 quad_perm:[2,3,0,1] row_mask:0xf bank_mask:0xf bound_ctrl:1
	v_add_f32_dpp v135, v135, v135 quad_perm:[2,3,0,1] row_mask:0xf bank_mask:0xf bound_ctrl:1
	v_add_f32_dpp v128, v128, v128 row_half_mirror row_mask:0xf bank_mask:0xf bound_ctrl:1
	v_add_f32_dpp v129, v129, v129 row_half_mirror row_mask:0xf bank_mask:0xf bound_ctrl:1
	v_add_f32_dpp v130, v130, v130 row_half_mirror row_mask:0xf bank_mask:0xf bound_ctrl:1
	v_add_f32_dpp v131, v131, v131 row_half_mirror row_mask:0xf bank_mask:0xf bound_ctrl:1
	v_add_f32_dpp v132, v132, v132 row_half_mirror row_mask:0xf bank_mask:0xf bound_ctrl:1
	v_add_f32_dpp v133, v133, v133 row_half_mirror row_mask:0xf bank_mask:0xf bound_ctrl:1
	v_add_f32_dpp v134, v134, v134 row_half_mirror row_mask:0xf bank_mask:0xf bound_ctrl:1
	v_add_f32_dpp v135, v135, v135 row_half_mirror row_mask:0xf bank_mask:0xf bound_ctrl:1
	v_add_f32_dpp v128, v128, v128 row_mirror row_mask:0xf bank_mask:0xf bound_ctrl:1
	v_add_f32_dpp v129, v129, v129 row_mirror row_mask:0xf bank_mask:0xf bound_ctrl:1
	v_add_f32_dpp v130, v130, v130 row_mirror row_mask:0xf bank_mask:0xf bound_ctrl:1
	v_add_f32_dpp v131, v131, v131 row_mirror row_mask:0xf bank_mask:0xf bound_ctrl:1
	v_add_f32_dpp v132, v132, v132 row_mirror row_mask:0xf bank_mask:0xf bound_ctrl:1
	v_add_f32_dpp v133, v133, v133 row_mirror row_mask:0xf bank_mask:0xf bound_ctrl:1
	v_add_f32_dpp v134, v134, v134 row_mirror row_mask:0xf bank_mask:0xf bound_ctrl:1
	v_add_f32_dpp v135, v135, v135 row_mirror row_mask:0xf bank_mask:0xf bound_ctrl:1
	v_readlane_b32 s16, v128, 0
	v_readlane_b32 s31, v128, 16
	v_readlane_b32 s17, v128, 32
	v_readlane_b32 s30, v128, 48
	v_readlane_b32 s34, v129, 0
	v_readlane_b32 s42, v129, 16
	v_readlane_b32 s35, v129, 32
	v_readlane_b32 s41, v129, 48
	v_readlane_b32 s43, v130, 0
	v_readlane_b32 s46, v130, 16
	v_readlane_b32 s44, v130, 32
	v_readlane_b32 s45, v130, 48
	v_readlane_b32 s47, v131, 0
	v_readlane_b32 s50, v131, 16
	v_readlane_b32 s48, v131, 32
	v_readlane_b32 s49, v131, 48
	v_readlane_b32 s51, v132, 0
	v_readlane_b32 s55, v132, 16
	v_readlane_b32 s52, v132, 32
	v_readlane_b32 s53, v132, 48
	v_readlane_b32 s56, v133, 0
	v_readlane_b32 s73, v133, 16
	v_readlane_b32 s57, v133, 32
	v_readlane_b32 s72, v133, 48
	v_readlane_b32 s74, v134, 0
	v_readlane_b32 s83, v134, 16
	v_readlane_b32 s75, v134, 32
	v_readlane_b32 s82, v134, 48
	v_readlane_b32 s84, v135, 0
	v_readlane_b32 s87, v135, 16
	v_readlane_b32 s85, v135, 32
	v_readlane_b32 s86, v135, 48
	s_and_saveexec_b64 s[28:29], vcc
	s_cbranch_execz .LBB0_188
	v_mov_b32_e32 v134, s42
	v_mov_b32_e32 v135, s31
	v_mov_b32_e32 v133, s46
	v_add_f32_e32 v134, s34, v134
	v_add_f32_e32 v135, s16, v135
	v_mov_b32_e32 v132, s50
	v_add_f32_e32 v133, s43, v133
	v_add_f32_e32 v134, s35, v134
	v_add_f32_e32 v135, s17, v135
	v_mov_b32_e32 v131, s55
	v_add_f32_e32 v132, s47, v132
	v_add_f32_e32 v133, s44, v133
	v_add_f32_e32 v134, s41, v134
	v_add_f32_e32 v135, s30, v135
	v_mov_b32_e32 v130, s73
	v_add_f32_e32 v131, s51, v131
	v_add_f32_e32 v132, s48, v132
	v_add_f32_e32 v133, s45, v133
	v_cndmask_b32_e64 v134, v135, v134, s[0:1]
	v_mov_b32_e32 v129, s83
	v_add_f32_e32 v130, s56, v130
	v_add_f32_e32 v131, s52, v131
	v_add_f32_e32 v132, s49, v132
	v_cndmask_b32_e64 v133, v134, v133, s[14:15]
	v_mov_b32_e32 v128, s87
	v_add_f32_e32 v129, s74, v129
	v_add_f32_e32 v130, s57, v130
	v_add_f32_e32 v131, s53, v131
	v_cndmask_b32_e64 v132, v133, v132, s[4:5]
	v_add_f32_e32 v128, s84, v128
	v_add_f32_e32 v129, s75, v129
	v_add_f32_e32 v130, s72, v130
	v_cndmask_b32_e64 v131, v132, v131, s[6:7]
	v_add_f32_e32 v128, s85, v128
	v_add_f32_e32 v129, s82, v129
	v_cndmask_b32_e64 v130, v131, v130, s[8:9]
	v_add_f32_e32 v128, s86, v128
	v_cndmask_b32_e64 v129, v130, v129, s[10:11]
	v_cndmask_b32_e64 v128, v129, v128, s[12:13]
	v_mov_b32_e32 v129, v251
	v_add_f32_e32 v128, v128, v129
	s_and_saveexec_b64 s[30:31], s[24:25]
	s_cbranch_execz .LBB0_187
	v_cmp_ngt_f32_e64 s[16:17], 0, v128
	s_and_saveexec_b64 s[34:35], s[16:17]
	s_xor_b64 s[34:35], exec, s[34:35]
	s_cbranch_execz .LBB0_217
; DI float logsig(float x) { return (x < 0.f) ? (x - log1pf(__expf(x))) : (-log1pf(__expf(-x))); }
; DI void phase1(const Params& p, unsigned char* smem) {
;     ...
;                 const int b = row >> 13, sidx = row & 8191;
;                 if (lane < 4) ig[(size_t)(b * 4 + lane) * 8192 + sidx] = val;
;                 else lf[(size_t)(b * 4 + lane - 4) * 8192 + sidx] = logsig(val);
	v_mul_f32_e32 v128, 0xbfb8aa3b, v128
	v_exp_f32_e32 v142, v128
	s_nop 0
	v_add_f32_e32 v130, 1.0, v142
	v_frexp_mant_f32_e32 v132, v130
	v_cvt_f64_f32_e32 v[128:129], v130
	v_frexp_exp_i32_f64_e32 v128, v[128:129]
	v_cmp_gt_f32_e64 s[16:17], s37, v132
	v_add_f32_e32 v131, -1.0, v130
	v_sub_f32_e32 v133, v131, v130
	v_subbrev_co_u32_e64 v136, s[16:17], 0, v128, s[16:17]
	v_sub_u32_e32 v128, 0, v136
	v_sub_f32_e32 v131, v142, v131
	v_add_f32_e32 v133, 1.0, v133
	v_ldexp_f32 v129, v130, v128
	v_add_f32_e32 v131, v131, v133
	v_add_f32_e32 v130, -1.0, v129
	v_add_f32_e32 v132, 1.0, v129
	v_ldexp_f32 v128, v131, v128
	v_add_f32_e32 v131, 1.0, v130
	v_add_f32_e32 v133, -1.0, v132
	v_sub_f32_e32 v131, v129, v131
	v_sub_f32_e32 v129, v129, v133
	v_add_f32_e32 v131, v128, v131
	v_add_f32_e32 v128, v128, v129
	v_add_f32_e32 v137, v132, v128
	v_rcp_f32_e32 v139, v137
	v_sub_f32_e32 v129, v137, v132
	v_sub_f32_e32 v138, v128, v129
	v_add_f32_e32 v129, v130, v131
	v_mul_f32_e32 v141, v129, v139
	v_sub_f32_e32 v128, v129, v130
	v_mul_f32_e32 v130, v137, v141
	v_fma_f32 v132, v141, v137, -v130
	v_fmac_f32_e32 v132, v141, v138
	v_sub_f32_e32 v140, v131, v128
	v_add_f32_e32 v128, v130, v132
	v_sub_f32_e32 v131, v129, v128
	v_pk_add_f32 v[134:135], v[128:129], v[130:131] neg_lo:[0,1] neg_hi:[0,1]
	v_mov_b32_e32 v133, v128
	v_pk_add_f32 v[128:129], v[134:135], v[132:133] neg_lo:[0,1] neg_hi:[0,1]
	v_cmp_neq_f32_e64 s[16:17], s39, v142
	v_add_f32_e32 v129, v140, v129
	v_add_f32_e32 v128, v128, v129
	v_add_f32_e32 v129, v131, v128
	v_mul_f32_e32 v140, v139, v129
	v_mul_f32_e32 v130, v137, v140
	v_fma_f32 v132, v140, v137, -v130
	v_fmac_f32_e32 v132, v140, v138
	v_sub_f32_e32 v131, v131, v129
	v_add_f32_e32 v137, v128, v131
	v_add_f32_e32 v128, v130, v132
	v_sub_f32_e32 v131, v129, v128
	v_pk_add_f32 v[134:135], v[128:129], v[130:131] neg_lo:[0,1] neg_hi:[0,1]
	v_mov_b32_e32 v133, v128
	v_pk_add_f32 v[128:129], v[134:135], v[132:133] neg_lo:[0,1] neg_hi:[0,1]
	s_nop 0
	v_add_f32_e32 v129, v137, v129
	v_add_f32_e32 v128, v128, v129
	v_add_f32_e32 v129, v141, v140
	v_add_f32_e32 v128, v131, v128
	v_sub_f32_e32 v130, v129, v141
	v_mul_f32_e32 v128, v139, v128
	v_sub_f32_e32 v130, v140, v130
	v_add_f32_e32 v130, v130, v128
	v_add_f32_e32 v132, v129, v130
	v_mul_f32_e32 v133, v132, v132
	v_fmamk_f32 v128, v133, 0x3e9b6dac, v233
	v_fmaak_f32 v193, v133, v128, 0x3f2aaada
	v_cvt_f32_i32_e32 v128, v136
	v_sub_f32_e32 v129, v132, v129
	v_sub_f32_e32 v129, v130, v129
	v_ldexp_f32 v134, v129, 1
	v_mul_f32_e32 v129, v132, v133
	v_ldexp_f32 v131, v132, 1
	v_pk_mul_f32 v[132:133], v[128:129], v[192:193]
	s_nop 0
	v_fma_f32 v130, v128, s38, -v132
	v_fmac_f32_e32 v130, 0xb102e308, v128
	v_pk_add_f32 v[128:129], v[132:133], v[130:131]
	s_nop 0
	v_sub_f32_e32 v131, v129, v131
	v_sub_f32_e32 v131, v133, v131
	v_add_f32_e32 v135, v134, v131
	v_mov_b32_e32 v134, v132
	v_pk_add_f32 v[132:133], v[128:129], v[132:133] neg_lo:[0,1] neg_hi:[0,1]
	v_pk_add_f32 v[136:137], v[128:129], v[134:135]
	v_mov_b32_e32 v131, v128
	v_mov_b32_e32 v133, v137
	v_pk_add_f32 v[138:139], v[130:131], v[132:133] neg_lo:[0,1] neg_hi:[0,1]
	v_pk_add_f32 v[130:131], v[130:131], v[132:133]
	v_mov_b32_e32 v134, v135
	v_pk_add_f32 v[132:133], v[130:131], v[128:129] op_sel:[1,0] op_sel_hi:[0,1] neg_lo:[0,1] neg_hi:[0,1]
	v_pk_add_f32 v[140:141], v[136:137], v[132:133] op_sel_hi:[1,0] neg_lo:[0,1] neg_hi:[0,1]
	v_mov_b32_e32 v136, v137
	v_mov_b32_e32 v137, v131
	v_pk_mov_b32 v[132:133], v[128:129], v[132:133] op_sel:[1,0]
	v_mov_b32_e32 v135, v128
	v_pk_add_f32 v[132:133], v[136:137], v[132:133] neg_lo:[0,1] neg_hi:[0,1]
	v_mov_b32_e32 v140, v138
	v_pk_add_f32 v[128:129], v[134:135], v[132:133] neg_lo:[0,1] neg_hi:[0,1]
	v_mov_b32_e32 v139, v131
	v_pk_add_f32 v[132:133], v[140:141], v[128:129]
	s_nop 0
	v_pk_add_f32 v[134:135], v[132:133], v[132:133] op_sel:[0,1] op_sel_hi:[1,0]
	s_nop 0
	v_pk_add_f32 v[130:131], v[130:131], v[134:135] op_sel:[1,0] op_sel_hi:[0,1]
	v_mov_b32_e32 v133, v130
	v_pk_add_f32 v[136:137], v[132:133], v[138:139] neg_lo:[0,1] neg_hi:[0,1]
	v_mov_b32_e32 v129, v134
	v_sub_f32_e32 v131, v132, v136
	v_pk_add_f32 v[128:129], v[128:129], v[136:137] neg_lo:[0,1] neg_hi:[0,1]
	v_sub_f32_e32 v131, v138, v131
	v_add_f32_e32 v128, v128, v131
	v_add_f32_e32 v128, v128, v129
	v_add_f32_e32 v128, v130, v128
	v_cndmask_b32_e64 v128, v234, v128, s[16:17]
	v_cmp_ngt_f32_e64 s[16:17], -1.0, v142
	s_nop 1
	v_cndmask_b32_e64 v128, v235, v128, s[16:17]
	v_cmp_neq_f32_e64 s[16:17], -1.0, v142
	s_nop 1
	v_cndmask_b32_e64 v128, v236, v128, s[16:17]
	v_cmp_lt_f32_e64 s[16:17], |v142|, s40
	s_nop 1
	v_cndmask_b32_e64 v128, v128, v142, s[16:17]
	v_xor_b32_e32 v128, 0x80000000, v128
